# attention softmax: skip alpha/rescale math when no row max moved, folded sum init, dropped duplicate vmcnt; plus earlier rcp-based silu and canonicalizing-max removal
# speedup vs baseline: 1.0142x; 1.0142x over previous
; DEV void finishSM(f32x16& p0, f32x16& p1, float alpha, float& l_reg, bf16x8& pa0, bf16x8& pa1, bf16x8& pa2, bf16x8& pa3) {
; #pragma unroll
;   for (int r = 0; r < 16; ++r) p1[r] = __builtin_amdgcn_exp2f(p1[r]);
;   float ps = 0;
; #pragma unroll
;   for (int r = 0; r < 16; ++r) ps += p0[r];
; #pragma unroll
;   for (int r = 0; r < 16; ++r) ps += p1[r];
;   { auto rr = __builtin_amdgcn_permlane32_swap(__float_as_uint(ps), __float_as_uint(ps), false, false);
;     ps = __uint_as_float(rr[0]) + __uint_as_float(rr[1]); }
;   l_reg = l_reg * alpha + ps;
;     ...
;   PK4(p0, 0, pa0); PK4(p0, 8, pa1); PK4(p1, 0, pa2); PK4(p1, 8, pa3);
;     ...
; }
; DEV void qkt(f32x16& p0, f32x16& p1, const char* Ks, const bf16x8* qr, int r32, int hi) {
;   p0 = f32x16{}; p1 = f32x16{};
; #pragma unroll
;   for (int d0 = 0; d0 < 4; ++d0) { int cb = (d0 * 16 + hi * 8) * 2;
;     bf16x8 b0 = *reinterpret_cast<const bf16x8*>(Ks + KSWZ64(r32, cb));
;     bf16x8 b1 = *reinterpret_cast<const bf16x8*>(Ks + KSWZ64(32 + r32, cb));
;     p0 = __builtin_amdgcn_mfma_f32_32x32x16_bf16(b0, qr[d0], p0, 0, 0, 0);
;     p1 = __builtin_amdgcn_mfma_f32_32x32x16_bf16(b1, qr[d0], p1, 0, 0, 0); }
; }
; DEV int v_st(int k, int c) { const int kk = (k & ~0xC) | ((k & 4) << 1) | ((k & 8) >> 1); return ((kk >> 3) * 4 + (c >> 5)) * 512 + ((kk & 7) * 32 + (c & 31)) * 2; }
; DEV int v_rd_base(int lane) { return ((lane & 3) << 3) | (((lane >> 2) & 3) << 6) | (((lane >> 4) & 1) << 5) | (((lane >> 5) & 1) << 8); }
; template <int OFF> DEV s16x4 tr_read(int vb) {
;   s16x4 r; asm volatile("ds_read_b64_tr_b16 %0, %1 offset:%2" : "=&v"(r) : "v"(vb), "i"(OFF) : "memory"); return r;
; }
; template <int D0> DEV void pv_one(f32x16& od, int vb, bf16x8 pa0, bf16x8 pa1, bf16x8 pa2, bf16x8 pa3) {
;   const s16x4 l0 = tr_read<v_rd_off(D0, 0, 0)>(vb), h0 = tr_read<v_rd_off(D0, 0, 1)>(vb), l1 = tr_read<v_rd_off(D0, 1, 0)>(vb), h1 = tr_read<v_rd_off(D0, 1, 1)>(vb);
;   const s16x4 l2 = tr_read<v_rd_off(D0, 2, 0)>(vb), h2 = tr_read<v_rd_off(D0, 2, 1)>(vb), l3 = tr_read<v_rd_off(D0, 3, 0)>(vb), h3 = tr_read<v_rd_off(D0, 3, 1)>(vb);
;   asm volatile("s_waitcnt lgkmcnt(0)" ::: "memory"); SBAR();
;     ...
;   od = __builtin_amdgcn_mfma_f32_32x32x16_bf16(pa0, PK(l0, h0), od, 0, 0, 0);
;   od = __builtin_amdgcn_mfma_f32_32x32x16_bf16(pa1, PK(l1, h1), od, 0, 0, 0);
;   od = __builtin_amdgcn_mfma_f32_32x32x16_bf16(pa2, PK(l2, h2), od, 0, 0, 0);
.LBB0_70:
	s_mul_hi_u32 s1, s9, 0xaaaaaaab
	s_lshr_b32 s1, s1, 1
	s_mul_i32 s1, s1, 0xc000
	v_subrev_u32_e32 v190, s1, v184
	s_mul_hi_u32 s1, s51, 0xaaaaaaab
	s_mul_hi_u32 s0, s66, 0xaaaaaaab
	s_lshr_b32 s12, s1, 1
	s_lshr_b32 s0, s0, 1
	s_mul_i32 s1, s12, 0x6000
	s_mul_i32 s15, s0, 0x6000
	v_subrev_u32_e32 v64, s1, v198
	s_mul_i32 s0, s0, 0xc000
	v_subrev_u32_e32 v216, s15, v180
	v_subrev_u32_e32 v164, s1, v200
	v_subrev_u32_e32 v217, s0, v203
	v_subrev_u32_e32 v218, s0, v204
	v_subrev_u32_e32 v191, s1, v209
	v_subrev_u32_e32 v192, s1, v210
	v_add_u32_e32 v141, s14, v181
	v_add_u32_e32 v68, v141, v64
	ds_read_b128 v[64:67], v68
	ds_read_b128 v[68:71], v68 offset:4096
	v_add_u32_e32 v186, v141, v164
	ds_read_b128 v[164:167], v186
	ds_read_b128 v[186:189], v186 offset:4096
	v_exp_f32_e32 v134, v134
	s_waitcnt lgkmcnt(3)
	v_mfma_f32_32x32x16_bf16 v[80:95], v[64:67], v[108:111], 0
	v_exp_f32_e32 v135, v135
	v_exp_f32_e32 v132, v132
	v_exp_f32_e32 v133, v133
	v_exp_f32_e32 v130, v130
	v_exp_f32_e32 v131, v131
	v_exp_f32_e32 v128, v128
	v_exp_f32_e32 v129, v129
	s_waitcnt lgkmcnt(2)
	v_mfma_f32_32x32x16_bf16 v[64:79], v[68:71], v[108:111], 0
	v_exp_f32_e32 v126, v126
	v_exp_f32_e32 v127, v127
	v_exp_f32_e32 v124, v124
	v_exp_f32_e32 v125, v125
	s_waitcnt lgkmcnt(1)
	v_mfma_f32_32x32x16_bf16 v[80:95], v[164:167], v[104:107], v[80:95]
	s_waitcnt lgkmcnt(0)
	v_mfma_f32_32x32x16_bf16 v[64:79], v[186:189], v[104:107], v[64:79]
	v_add_u32_e32 v186, v141, v191
	ds_read_b128 v[164:167], v186
	ds_read_b128 v[186:189], v186 offset:4096
	s_waitcnt lgkmcnt(1)
	v_mfma_f32_32x32x16_bf16 v[80:95], v[164:167], v[100:103], v[80:95]
	s_waitcnt lgkmcnt(0)
	v_mfma_f32_32x32x16_bf16 v[64:79], v[186:189], v[100:103], v[64:79]
	v_add_u32_e32 v186, v141, v192
	ds_read_b128 v[164:167], v186
	ds_read_b128 v[186:189], v186 offset:4096
	s_waitcnt lgkmcnt(1)
	v_mfma_f32_32x32x16_bf16 v[80:95], v[164:167], v[96:99], v[80:95]
	v_exp_f32_e32 v166, v136
	v_add_f32_e32 v136, v160, v150
	v_add_f32_e32 v136, v151, v136
	v_add_f32_e32 v136, v161, v136
	v_add_f32_e32 v136, v158, v136
	v_add_f32_e32 v136, v214, v136
	v_add_f32_e32 v136, v159, v136
	v_add_f32_e32 v136, v215, v136
	v_add_f32_e32 v136, v142, v136
	v_add_f32_e32 v136, v146, v136
	v_add_f32_e32 v136, v143, v136
	v_add_f32_e32 v136, v147, v136
	v_exp_f32_e32 v164, v138
	v_add_f32_e32 v136, v144, v136
	v_exp_f32_e32 v165, v139
	v_add_f32_e32 v136, v148, v136
	v_add_f32_e32 v136, v145, v136
	v_exp_f32_e32 v167, v137
	v_add_f32_e32 v136, v149, v136
	v_add_f32_e32 v136, v164, v136
	v_add_f32_e32 v136, v165, v136
	v_add_f32_e32 v136, v166, v136
	v_add_f32_e32 v136, v167, v136
	v_add_f32_e32 v136, v134, v136
	v_add_f32_e32 v136, v135, v136
	v_add_f32_e32 v136, v132, v136
	v_add_f32_e32 v136, v133, v136
	v_add_f32_e32 v136, v130, v136
	v_add_f32_e32 v136, v131, v136
	s_waitcnt lgkmcnt(0)
	v_mfma_f32_32x32x16_bf16 v[64:79], v[186:189], v[96:99], v[64:79]
	v_add_f32_e32 v136, v128, v136
	v_add_f32_e32 v136, v129, v136
	v_add_f32_e32 v136, v126, v136
	v_add_f32_e32 v136, v127, v136
	v_add_f32_e32 v136, v124, v136
	v_add_f32_e32 v211, v125, v136
	v_mov_b32_e32 v212, v211
	v_cvt_pk_bf16_f32 v136, v150, v160
	v_cvt_pk_bf16_f32 v138, v158, v214
	s_nop 1
	v_permlane32_swap_b32_e32 v211, v212
	v_cvt_pk_bf16_f32 v137, v151, v161
	v_cvt_pk_bf16_f32 v139, v159, v215
	v_permlane32_swap_b32_e32 v136, v138
	v_cvt_pk_bf16_f32 v142, v142, v146
	v_cvt_pk_bf16_f32 v143, v143, v147
	v_cvt_pk_bf16_f32 v144, v144, v148
	v_cvt_pk_bf16_f32 v145, v145, v149
	v_cvt_pk_bf16_f32 v146, v164, v165
	v_cvt_pk_bf16_f32 v147, v166, v167
	v_cvt_pk_bf16_f32 v148, v134, v135
	v_cvt_pk_bf16_f32 v149, v132, v133
	v_cvt_pk_bf16_f32 v164, v130, v131
	v_cvt_pk_bf16_f32 v165, v128, v129
	v_cvt_pk_bf16_f32 v166, v126, v127
	v_cvt_pk_bf16_f32 v167, v124, v125
	v_permlane32_swap_b32_e32 v137, v139
	v_permlane32_swap_b32_e32 v142, v144
	v_permlane32_swap_b32_e32 v143, v145
	v_permlane32_swap_b32_e32 v146, v148
	v_permlane32_swap_b32_e32 v147, v149
	v_permlane32_swap_b32_e32 v164, v166
	v_permlane32_swap_b32_e32 v165, v167
	v_lshl_add_u64 v[158:159], v[156:157], 0, s[82:83]
	v_add_co_u32_e32 v124, vcc, s94, v158
	v_lshl_add_u64 v[160:161], v[154:155], 0, s[82:83]
	s_nop 0
	v_addc_co_u32_e32 v125, vcc, 0, v159, vcc
	v_add_co_u32_e32 v128, vcc, s95, v158
	s_mov_b32 s0, 0x18606000
	s_nop 0
	v_addc_co_u32_e32 v129, vcc, 0, v159, vcc
	v_add_co_u32_e32 v132, vcc, s0, v160
	global_load_dwordx4 v[124:127], v[124:125], off
	s_nop 0
	global_load_dwordx4 v[128:131], v[128:129], off
	v_addc_co_u32_e32 v133, vcc, 0, v161, vcc
	global_load_dwordx4 v[132:135], v[132:133], off
	v_add_u32_e32 v150, s8, v190
	ds_read_b64_tr_b16 v[186:187], v150 offset:0
	ds_read_b64_tr_b16 v[188:189], v150 offset:0x800
	ds_read_b64_tr_b16 v[190:191], v150 offset:0x1000
	ds_read_b64_tr_b16 v[192:193], v150 offset:0x1800
	ds_read_b64_tr_b16 v[220:221], v150 offset:0x2000
	ds_read_b64_tr_b16 v[222:223], v150 offset:0x2800
	ds_read_b64_tr_b16 v[224:225], v150 offset:0x3000
	ds_read_b64_tr_b16 v[226:227], v150 offset:0x3800
	s_waitcnt lgkmcnt(0)
	s_nop 0
	v_mfma_f32_32x32x16_bf16 v[0:15], v[136:139], v[186:189], v[0:15]
	ds_read_b64_tr_b16 v[186:187], v150 offset:0x200
	ds_read_b64_tr_b16 v[188:189], v150 offset:0xa00
	v_mfma_f32_32x32x16_bf16 v[0:15], v[142:145], v[190:193], v[0:15]
	ds_read_b64_tr_b16 v[190:191], v150 offset:0x1200
	ds_read_b64_tr_b16 v[192:193], v150 offset:0x1a00
	v_mfma_f32_32x32x16_bf16 v[0:15], v[146:149], v[220:223], v[0:15]
	ds_read_b64_tr_b16 v[220:221], v150 offset:0x2200
	ds_read_b64_tr_b16 v[222:223], v150 offset:0x2a00
	v_mfma_f32_32x32x16_bf16 v[0:15], v[164:167], v[224:227], v[0:15]
	ds_read_b64_tr_b16 v[224:225], v150 offset:0x3200
	ds_read_b64_tr_b16 v[226:227], v150 offset:0x3a00
	s_waitcnt lgkmcnt(0)
; DEV void partialSM(f32x16& p0, f32x16& p1, float& m_reg, float& mn, float& alpha) {
;   constexpr float C = AT_SCALE * 1.4426950408889634f;
;   float pmax = p0[0];
; #pragma unroll
;   for (int r = 1; r < 16; ++r) pmax = fmaxf(pmax, p0[r]);
; #pragma unroll
;   for (int r = 0; r < 16; ++r) pmax = fmaxf(pmax, p1[r]);
;   { auto rr = __builtin_amdgcn_permlane32_swap(__float_as_uint(pmax), __float_as_uint(pmax), false, false);
;     pmax = fmaxf(__uint_as_float(rr[0]), __uint_as_float(rr[1])); }
;   if (__builtin_expect(__all(pmax - m_reg <= AT_THR / AT_SCALE), 1)) { mn = m_reg; alpha = 1.f; }
;   else { mn = fmaxf(m_reg, pmax); alpha = __builtin_amdgcn_exp2f((m_reg - mn) * C); m_reg = mn; }
; template <int D0> DEV void pv_one(f32x16& od, int vb, bf16x8 pa0, bf16x8 pa1, bf16x8 pa2, bf16x8 pa3) {
;   const s16x4 l0 = tr_read<v_rd_off(D0, 0, 0)>(vb), h0 = tr_read<v_rd_off(D0, 0, 1)>(vb), l1 = tr_read<v_rd_off(D0, 1, 0)>(vb), h1 = tr_read<v_rd_off(D0, 1, 1)>(vb);
;   const s16x4 l2 = tr_read<v_rd_off(D0, 2, 0)>(vb), h2 = tr_read<v_rd_off(D0, 2, 1)>(vb), l3 = tr_read<v_rd_off(D0, 3, 0)>(vb), h3 = tr_read<v_rd_off(D0, 3, 1)>(vb);
;   asm volatile("s_waitcnt lgkmcnt(0)" ::: "memory"); SBAR();
;     ...
;   od = __builtin_amdgcn_mfma_f32_32x32x16_bf16(pa0, PK(l0, h0), od, 0, 0, 0);
;   od = __builtin_amdgcn_mfma_f32_32x32x16_bf16(pa1, PK(l1, h1), od, 0, 0, 0);
;   od = __builtin_amdgcn_mfma_f32_32x32x16_bf16(pa2, PK(l2, h2), od, 0, 0, 0);
;   od = __builtin_amdgcn_mfma_f32_32x32x16_bf16(pa3, PK(l3, h3), od, 0, 0, 0);
;     ...
; }
; DEV void pv_d0(f32x16* o, int vb, bf16x8 pa0, bf16x8 pa1, bf16x8 pa2, bf16x8 pa3) {
;   pv_one<0>(o[0], vb, pa0, pa1, pa2, pa3); pv_one<1>(o[1], vb, pa0, pa1, pa2, pa3); pv_one<2>(o[2], vb, pa0, pa1, pa2, pa3); pv_one<3>(o[3], vb, pa0, pa1, pa2, pa3);
; }
; DEV void attn_pass(const u16* __restrict__ Qb, const u16* __restrict__ Kh, const u16* __restrict__ Vh, int seq, f32x16* o, float* rli) {
;   char* lds = g_shm;
;   const int tid = ltid(), wid = tid >> 6, lane = tid & 63, r32 = lane & 31, hi = lane >> 5;
;   char* V_lds = lds; char* K_lds = lds + 3 * AT_SHM_V;
;   float* wsx = (float*)(lds + 3 * AT_SHM_V + 3 * AT_SHM_K) + wid * 64; float* li_l = wsx; float* al_l = wsx + 32;
;   float m_reg = -1e30f, l_reg = 0; bf16x8 qr[4];
; #pragma unroll
;   for (int d = 0; d < 4; ++d) o[d] = f32x16{};
;   const u16* Qw = Qb + (size_t)(wid * 32 + r32) * 64 + hi * 8;
	v_mfma_f32_32x32x16_bf16 v[48:63], v[136:139], v[186:189], v[48:63]
	ds_read_b64_tr_b16 v[186:187], v150 offset:0x400
	ds_read_b64_tr_b16 v[188:189], v150 offset:0xc00
	v_mfma_f32_32x32x16_bf16 v[48:63], v[142:145], v[190:193], v[48:63]
	ds_read_b64_tr_b16 v[190:191], v150 offset:0x1400
	ds_read_b64_tr_b16 v[192:193], v150 offset:0x1c00
	v_mfma_f32_32x32x16_bf16 v[48:63], v[146:149], v[220:223], v[48:63]
	ds_read_b64_tr_b16 v[220:221], v150 offset:0x2400
	ds_read_b64_tr_b16 v[222:223], v150 offset:0x2c00
	v_mfma_f32_32x32x16_bf16 v[48:63], v[164:167], v[224:227], v[48:63]
	ds_read_b64_tr_b16 v[224:225], v150 offset:0x3400
	ds_read_b64_tr_b16 v[226:227], v150 offset:0x3c00
	s_waitcnt lgkmcnt(0)
	v_mfma_f32_32x32x16_bf16 v[32:47], v[136:139], v[186:189], v[32:47]
	ds_read_b64_tr_b16 v[186:187], v150 offset:0x600
	ds_read_b64_tr_b16 v[188:189], v150 offset:0xe00
	v_mfma_f32_32x32x16_bf16 v[32:47], v[142:145], v[190:193], v[32:47]
	ds_read_b64_tr_b16 v[190:191], v150 offset:0x1600
	ds_read_b64_tr_b16 v[192:193], v150 offset:0x1e00
	v_mfma_f32_32x32x16_bf16 v[32:47], v[146:149], v[220:223], v[32:47]
	ds_read_b64_tr_b16 v[220:221], v150 offset:0x2600
	ds_read_b64_tr_b16 v[222:223], v150 offset:0x2e00
	v_mfma_f32_32x32x16_bf16 v[32:47], v[164:167], v[224:227], v[32:47]
	ds_read_b64_tr_b16 v[224:225], v150 offset:0x3600
	ds_read_b64_tr_b16 v[226:227], v150 offset:0x3e00
	s_waitcnt lgkmcnt(0)
	v_mfma_f32_32x32x16_bf16 v[16:31], v[136:139], v[186:189], v[16:31]
	v_max_f32_e32 v136, v80, v81
	v_max3_f32 v136, v136, v82, v83
	v_max3_f32 v136, v136, v84, v85
	v_max3_f32 v136, v136, v86, v87
	v_max3_f32 v136, v136, v88, v89
	v_max3_f32 v136, v136, v90, v91
	v_max3_f32 v136, v136, v92, v93
	v_max3_f32 v136, v136, v94, v95
	v_mfma_f32_32x32x16_bf16 v[16:31], v[142:145], v[190:193], v[16:31]
	v_max3_f32 v136, v136, v64, v65
	v_max3_f32 v136, v136, v66, v67
	v_max3_f32 v136, v136, v68, v69
	v_max3_f32 v136, v136, v70, v71
	v_max3_f32 v136, v136, v72, v73
	v_max3_f32 v136, v136, v74, v75
	v_max3_f32 v136, v136, v76, v77
	v_max3_f32 v136, v136, v78, v79
	v_mfma_f32_32x32x16_bf16 v[16:31], v[146:149], v[220:223], v[16:31]
	v_mov_b32_e32 v137, v136
	s_nop 1
	v_permlane32_swap_b32_e32 v136, v137
	v_max_f32_e32 v136, v136, v137
	v_sub_f32_e32 v137, v136, v140
	v_cmp_ge_f32_e32 vcc, s18, v137
	v_mfma_f32_32x32x16_bf16 v[16:31], v[164:167], v[224:227], v[16:31]
	s_cmp_eq_u64 vcc, exec
	s_cselect_b64 s[0:1], -1, 0
	s_cbranch_scc1 .Lattn_fast1
	v_max_f32_e32 v136, v140, v136
	v_sub_f32_e32 v137, v140, v136
	v_mul_f32_e32 v137, 0x3e38aa3b, v137
	v_exp_f32_e32 v137, v137
.Lattn_fast1:
	v_add_u32_e32 v214, s8, v202
	v_cndmask_b32_e64 v213, v137, 1.0, s[0:1]
	s_waitcnt vmcnt(3)
	v_add_u32_e32 v137, v214, v218
	ds_write_b128 v137, v[116:119]
	v_add_u32_e32 v137, v214, v217
	s_add_i32 s13, s14, 0
	ds_write_b128 v137, v[112:115]
	v_add_u32_e32 v137, s13, v216
	v_cmp_gt_f32_e32 vcc, 1.0, v213
	ds_write_b128 v137, v[120:123]
	s_cbranch_vccz .LBB0_74
	s_and_saveexec_b64 s[10:11], s[6:7]
	ds_write_b32 v169, v213 offset:128
	s_or_b64 exec, exec, s[10:11]
	s_waitcnt lgkmcnt(0)
	v_add_u32_e32 v137, v168, v162
	ds_read_b128 v[142:145], v137 offset:224
	ds_read_b128 v[146:149], v137 offset:192
	ds_read_b128 v[164:167], v137 offset:160
	ds_read_b128 v[186:189], v137 offset:128
	s_waitcnt lgkmcnt(3)
	v_pk_mul_f32 v[12:13], v[12:13], v[142:143]
	s_waitcnt lgkmcnt(2)
	v_pk_mul_f32 v[8:9], v[8:9], v[146:147]
	s_waitcnt lgkmcnt(1)
	v_pk_mul_f32 v[4:5], v[4:5], v[164:165]
	v_pk_mul_f32 v[14:15], v[14:15], v[144:145]
	v_pk_mul_f32 v[10:11], v[10:11], v[148:149]
	v_pk_mul_f32 v[6:7], v[6:7], v[166:167]
	s_waitcnt lgkmcnt(0)
	v_pk_mul_f32 v[2:3], v[2:3], v[188:189]
	v_pk_mul_f32 v[0:1], v[0:1], v[186:187]
	v_pk_mul_f32 v[60:61], v[60:61], v[142:143]
	v_pk_mul_f32 v[56:57], v[56:57], v[146:147]
	v_pk_mul_f32 v[52:53], v[52:53], v[164:165]
	v_pk_mul_f32 v[62:63], v[62:63], v[144:145]
	v_pk_mul_f32 v[58:59], v[58:59], v[148:149]
	v_pk_mul_f32 v[54:55], v[54:55], v[166:167]
	v_pk_mul_f32 v[50:51], v[50:51], v[188:189]
	v_pk_mul_f32 v[48:49], v[48:49], v[186:187]
	v_pk_mul_f32 v[44:45], v[44:45], v[142:143]
	v_pk_mul_f32 v[40:41], v[40:41], v[146:147]
	v_pk_mul_f32 v[36:37], v[36:37], v[164:165]
	v_pk_mul_f32 v[46:47], v[46:47], v[144:145]
	v_pk_mul_f32 v[42:43], v[42:43], v[148:149]
	v_pk_mul_f32 v[38:39], v[38:39], v[166:167]
	v_pk_mul_f32 v[34:35], v[34:35], v[188:189]
	v_pk_mul_f32 v[32:33], v[32:33], v[186:187]
	v_pk_mul_f32 v[28:29], v[28:29], v[142:143]
	v_pk_mul_f32 v[24:25], v[24:25], v[146:147]
	v_pk_mul_f32 v[20:21], v[20:21], v[164:165]
	v_pk_mul_f32 v[30:31], v[30:31], v[144:145]
	v_pk_mul_f32 v[26:27], v[26:27], v[148:149]
	v_pk_mul_f32 v[22:23], v[22:23], v[166:167]
	v_pk_mul_f32 v[18:19], v[18:19], v[188:189]
	v_pk_mul_f32 v[16:17], v[16:17], v[186:187]
; #define SBAR() __builtin_amdgcn_sched_barrier(0)
; #define SLOAD(i, k0) do { sr_[i].vs0 = *reinterpret_cast<const bf16x8*>(&Vh[(size_t)((k0) + sr) * 128 + sc]); sr_[i].vs1 = *reinterpret_cast<const bf16x8*>(&Vh[(size_t)((k0) + 32 + sr) * 128 + sc]); \
;     sr_[i].ks0 = *reinterpret_cast<const bf16x8*>(&Kh[(size_t)((k0) + kr) * 64 + kc]); } while (0)
; DEV void partialSM(f32x16& p0, f32x16& p1, float& m_reg, float& mn, float& alpha) {
;   constexpr float C = AT_SCALE * 1.4426950408889634f;
;   float pmax = p0[0];
; #pragma unroll
;   for (int r = 1; r < 16; ++r) pmax = fmaxf(pmax, p0[r]);
; #pragma unroll
;   for (int r = 0; r < 16; ++r) pmax = fmaxf(pmax, p1[r]);
;   { auto rr = __builtin_amdgcn_permlane32_swap(__float_as_uint(pmax), __float_as_uint(pmax), false, false);
;     pmax = fmaxf(__uint_as_float(rr[0]), __uint_as_float(rr[1])); }
;   if (__builtin_expect(__all(pmax - m_reg <= AT_THR / AT_SCALE), 1)) { mn = m_reg; alpha = 1.f; }
;   else { mn = fmaxf(m_reg, pmax); alpha = __builtin_amdgcn_exp2f((m_reg - mn) * C); m_reg = mn; }
;   float mnC = -mn * C;
; #pragma unroll
;   for (int r = 0; r < 16; ++r) p0[r] = fmaf(p0[r], C, mnC);
; #pragma unroll
;   for (int r = 0; r < 16; ++r) p1[r] = fmaf(p1[r], C, mnC);
; #pragma unroll
;   for (int r = 0; r < 16; ++r) p0[r] = __builtin_amdgcn_exp2f(p0[r]);
; }
; DEV void finishSM(f32x16& p0, f32x16& p1, float alpha, float& l_reg, bf16x8& pa0, bf16x8& pa1, bf16x8& pa2, bf16x8& pa3) {
; #pragma unroll
;   for (int r = 0; r < 16; ++r) p1[r] = __builtin_amdgcn_exp2f(p1[r]);
;   float ps = 0;
; #pragma unroll
;   for (int r = 0; r < 16; ++r) ps += p0[r];
; #pragma unroll
;   for (int r = 0; r < 16; ++r) ps += p1[r];
;   { auto rr = __builtin_amdgcn_permlane32_swap(__float_as_uint(ps), __float_as_uint(ps), false, false);
;     ps = __uint_as_float(rr[0]) + __uint_as_float(rr[1]); }
;   l_reg = l_reg * alpha + ps;
;     ...
;   PK4(p0, 0, pa0); PK4(p0, 8, pa1); PK4(p1, 0, pa2); PK4(p1, 8, pa3);
;     ...
; }
; DEV void attn_pass(const u16* __restrict__ Qb, const u16* __restrict__ Kh, const u16* __restrict__ Vh, int seq, f32x16* o, float* rli) {
;     ...
;     RESC(alB); __syncthreads();
;     SBAR(); qkt(pA0, pA1, K_lds + b1 * AT_SHM_K, qr, r32, hi);
;     finishSM(pB0, pB1, alB, l_reg, pa0, pa1, pa2, pa3); SBAR();
;     if (j + 3 < NT) SLOAD(SE, (j + 3) * 64); SBAR();
.LBB0_74:
	v_cndmask_b32_e64 v215, v136, v140, s[0:1]
	v_mul_f32_e32 v148, 0xbe38aa3b, v215
	v_subrev_u32_e32 v137, s15, v183
	v_subrev_u32_e32 v138, s15, v185
	v_subrev_u32_e32 v146, s15, v199
	v_subrev_u32_e32 v147, s15, v201
	v_fmamk_f32 v80, v80, 0x3e38aa3b, v148
	v_fmamk_f32 v81, v81, 0x3e38aa3b, v148
	v_fmamk_f32 v82, v82, 0x3e38aa3b, v148
	v_fmamk_f32 v83, v83, 0x3e38aa3b, v148
	v_fmamk_f32 v84, v84, 0x3e38aa3b, v148
	v_fmamk_f32 v85, v85, 0x3e38aa3b, v148
	v_fmamk_f32 v86, v86, 0x3e38aa3b, v148
	v_fmamk_f32 v87, v87, 0x3e38aa3b, v148
	v_fmamk_f32 v88, v88, 0x3e38aa3b, v148
	v_fmamk_f32 v89, v89, 0x3e38aa3b, v148
	v_fmamk_f32 v90, v90, 0x3e38aa3b, v148
	v_fmamk_f32 v91, v91, 0x3e38aa3b, v148
	v_fmamk_f32 v92, v92, 0x3e38aa3b, v148
	v_fmamk_f32 v93, v93, 0x3e38aa3b, v148
	v_fmamk_f32 v94, v94, 0x3e38aa3b, v148
	v_fmamk_f32 v95, v95, 0x3e38aa3b, v148
	v_fmamk_f32 v149, v64, 0x3e38aa3b, v148
	v_fmamk_f32 v150, v65, 0x3e38aa3b, v148
	v_fmamk_f32 v151, v66, 0x3e38aa3b, v148
	v_fmamk_f32 v164, v67, 0x3e38aa3b, v148
	v_fmamk_f32 v165, v68, 0x3e38aa3b, v148
	v_fmamk_f32 v166, v69, 0x3e38aa3b, v148
	v_fmamk_f32 v167, v70, 0x3e38aa3b, v148
	v_fmamk_f32 v186, v71, 0x3e38aa3b, v148
	v_fmamk_f32 v187, v72, 0x3e38aa3b, v148
	v_fmamk_f32 v188, v73, 0x3e38aa3b, v148
	v_fmamk_f32 v189, v74, 0x3e38aa3b, v148
	v_fmamk_f32 v190, v75, 0x3e38aa3b, v148
	v_fmamk_f32 v191, v76, 0x3e38aa3b, v148
	v_fmamk_f32 v192, v77, 0x3e38aa3b, v148
	v_fmamk_f32 v193, v78, 0x3e38aa3b, v148
	v_fmac_f32_e32 v148, 0x3e38aa3b, v79
	v_exp_f32_e32 v194, v80
	v_exp_f32_e32 v195, v81
	v_exp_f32_e32 v218, v82
	v_exp_f32_e32 v219, v83
	v_exp_f32_e32 v220, v84
	v_exp_f32_e32 v221, v85
	v_exp_f32_e32 v222, v86
	v_exp_f32_e32 v223, v87
	v_exp_f32_e32 v224, v88
	v_exp_f32_e32 v225, v89
	v_exp_f32_e32 v226, v90
	v_exp_f32_e32 v227, v91
	v_exp_f32_e32 v228, v92
	v_exp_f32_e32 v229, v93
	v_exp_f32_e32 v230, v94
	v_exp_f32_e32 v231, v95
	s_waitcnt lgkmcnt(0)
	s_barrier
	v_add_u32_e32 v68, v141, v137
	ds_read_b128 v[64:67], v68
	ds_read_b128 v[68:71], v68 offset:4096
	v_add_u32_e32 v140, v141, v138
	ds_read_b128 v[136:139], v140
	ds_read_b128 v[142:145], v140 offset:4096
	v_add_u32_e32 v140, v141, v146
	s_waitcnt lgkmcnt(3)
	v_mfma_f32_32x32x16_bf16 v[80:95], v[64:67], v[108:111], 0
	v_exp_f32_e32 v146, v151
	v_exp_f32_e32 v151, v167
	v_exp_f32_e32 v167, v189
	v_exp_f32_e32 v189, v193
	s_waitcnt lgkmcnt(2)
	v_mfma_f32_32x32x16_bf16 v[64:79], v[68:71], v[108:111], 0
	s_waitcnt lgkmcnt(1)
	v_mfma_f32_32x32x16_bf16 v[80:95], v[136:139], v[104:107], v[80:95]
	s_waitcnt lgkmcnt(0)
	v_mfma_f32_32x32x16_bf16 v[64:79], v[142:145], v[104:107], v[64:79]
	ds_read_b128 v[136:139], v140
	ds_read_b128 v[142:145], v140 offset:4096
	v_add_u32_e32 v140, v141, v147
	v_exp_f32_e32 v147, v164
	v_exp_f32_e32 v164, v186
	v_exp_f32_e32 v186, v190
	v_exp_f32_e32 v190, v148
	s_waitcnt lgkmcnt(1)
	v_mfma_f32_32x32x16_bf16 v[80:95], v[136:139], v[100:103], v[80:95]
	s_waitcnt lgkmcnt(0)
	v_mfma_f32_32x32x16_bf16 v[64:79], v[142:145], v[100:103], v[64:79]
	ds_read_b128 v[136:139], v140
	ds_read_b128 v[140:143], v140 offset:4096
	v_exp_f32_e32 v144, v149
	v_exp_f32_e32 v145, v150
	v_exp_f32_e32 v149, v165
	v_exp_f32_e32 v150, v166
	v_exp_f32_e32 v165, v187
	v_exp_f32_e32 v166, v188
	s_waitcnt lgkmcnt(1)
	v_mfma_f32_32x32x16_bf16 v[80:95], v[136:139], v[96:99], v[80:95]
	v_add_f32_e32 v136, v195, v194
	v_add_f32_e32 v136, v218, v136
	v_add_f32_e32 v136, v219, v136
	v_add_f32_e32 v136, v220, v136
	v_add_f32_e32 v136, v221, v136
	v_add_f32_e32 v136, v222, v136
	v_add_f32_e32 v136, v223, v136
	v_add_f32_e32 v136, v224, v136
	v_add_f32_e32 v136, v225, v136
	v_add_f32_e32 v136, v226, v136
	v_add_f32_e32 v136, v227, v136
	v_add_f32_e32 v136, v228, v136
	v_add_f32_e32 v136, v229, v136
	v_add_f32_e32 v136, v230, v136
	v_add_f32_e32 v136, v231, v136
	v_add_f32_e32 v136, v144, v136
	v_add_f32_e32 v136, v145, v136
	v_add_f32_e32 v136, v146, v136
	v_add_f32_e32 v136, v147, v136
	v_add_f32_e32 v136, v149, v136
	v_add_f32_e32 v136, v150, v136
	v_add_f32_e32 v136, v151, v136
	v_add_f32_e32 v136, v164, v136
	v_exp_f32_e32 v187, v191
	v_add_f32_e32 v136, v165, v136
	v_exp_f32_e32 v188, v192
	v_add_f32_e32 v136, v166, v136
	s_waitcnt lgkmcnt(0)
	v_mfma_f32_32x32x16_bf16 v[64:79], v[140:143], v[96:99], v[64:79]
	v_add_f32_e32 v136, v167, v136
	v_add_f32_e32 v136, v186, v136
	v_add_f32_e32 v136, v187, v136
	v_add_f32_e32 v136, v188, v136
	v_add_f32_e32 v136, v189, v136
	v_add_f32_e32 v216, v190, v136
	v_mov_b32_e32 v217, v216
	v_cvt_pk_bf16_f32 v136, v194, v195
	v_cvt_pk_bf16_f32 v137, v218, v219
	v_cvt_pk_bf16_f32 v138, v220, v221
	v_cvt_pk_bf16_f32 v139, v222, v223
	v_cvt_pk_bf16_f32 v140, v224, v225
	v_cvt_pk_bf16_f32 v141, v226, v227
	v_cvt_pk_bf16_f32 v142, v228, v229
	v_cvt_pk_bf16_f32 v143, v230, v231
	v_cvt_pk_bf16_f32 v144, v144, v145
	v_cvt_pk_bf16_f32 v145, v146, v147
	v_cvt_pk_bf16_f32 v146, v149, v150
	v_cvt_pk_bf16_f32 v147, v151, v164
	v_cvt_pk_bf16_f32 v148, v165, v166
	v_cvt_pk_bf16_f32 v149, v167, v186
	v_cvt_pk_bf16_f32 v150, v187, v188
	v_cvt_pk_bf16_f32 v151, v189, v190
	s_nop 1
	v_permlane32_swap_b32_e32 v216, v217
	v_permlane32_swap_b32_e32 v136, v138
	v_permlane32_swap_b32_e32 v137, v139
	v_permlane32_swap_b32_e32 v140, v142
	v_permlane32_swap_b32_e32 v141, v143
	v_permlane32_swap_b32_e32 v144, v146
	v_permlane32_swap_b32_e32 v145, v147
	v_permlane32_swap_b32_e32 v148, v150
	v_permlane32_swap_b32_e32 v149, v151
	s_cmp_ge_u32 s45, s44
	s_cselect_b64 s[10:11], -1, 0
	s_and_b64 vcc, exec, s[10:11]
	s_cbranch_vccnz .LBB0_76
	v_add_co_u32_e32 v112, vcc, 0x1a810000, v158
	s_nop 1
	v_addc_co_u32_e32 v113, vcc, 0, v159, vcc
	v_add_co_u32_e32 v114, vcc, 0x1a812000, v158
	s_nop 1
	v_addc_co_u32_e32 v115, vcc, 0, v159, vcc
	v_add_co_u32_e32 v120, vcc, 0x18608000, v160
	global_load_dwordx4 v[116:119], v[112:113], off
	s_nop 0
	global_load_dwordx4 v[112:115], v[114:115], off
	v_addc_co_u32_e32 v121, vcc, 0, v161, vcc
	global_load_dwordx4 v[120:123], v[120:121], off
; #define SBAR() __builtin_amdgcn_sched_barrier(0)
; #define SWRITE(b, i) do { *(bf16x8*)(V_lds + (b) * AT_SHM_V + vst0) = sr_[i].vs0; *(bf16x8*)(V_lds + (b) * AT_SHM_V + vst1) = sr_[i].vs1; \
;     *(bf16x8*)(K_lds + (b) * AT_SHM_K + kst) = sr_[i].ks0; } while (0)
; #define SWAIT() asm volatile("s_waitcnt vmcnt(3)" ::: "memory")
; template <int D0> DEV void pv_one(f32x16& od, int vb, bf16x8 pa0, bf16x8 pa1, bf16x8 pa2, bf16x8 pa3) {
;   const s16x4 l0 = tr_read<v_rd_off(D0, 0, 0)>(vb), h0 = tr_read<v_rd_off(D0, 0, 1)>(vb), l1 = tr_read<v_rd_off(D0, 1, 0)>(vb), h1 = tr_read<v_rd_off(D0, 1, 1)>(vb);
;   const s16x4 l2 = tr_read<v_rd_off(D0, 2, 0)>(vb), h2 = tr_read<v_rd_off(D0, 2, 1)>(vb), l3 = tr_read<v_rd_off(D0, 3, 0)>(vb), h3 = tr_read<v_rd_off(D0, 3, 1)>(vb);
;   asm volatile("s_waitcnt lgkmcnt(0)" ::: "memory"); SBAR();
;     ...
;   od = __builtin_amdgcn_mfma_f32_32x32x16_bf16(pa0, PK(l0, h0), od, 0, 0, 0);
;   od = __builtin_amdgcn_mfma_f32_32x32x16_bf16(pa1, PK(l1, h1), od, 0, 0, 0);
;   od = __builtin_amdgcn_mfma_f32_32x32x16_bf16(pa2, PK(l2, h2), od, 0, 0, 0);
;   od = __builtin_amdgcn_mfma_f32_32x32x16_bf16(pa3, PK(l3, h3), od, 0, 0, 0);
;     ...
; }
; DEV void pv_d0(f32x16* o, int vb, bf16x8 pa0, bf16x8 pa1, bf16x8 pa2, bf16x8 pa3) {
;   pv_one<0>(o[0], vb, pa0, pa1, pa2, pa3); pv_one<1>(o[1], vb, pa0, pa1, pa2, pa3); pv_one<2>(o[2], vb, pa0, pa1, pa2, pa3); pv_one<3>(o[3], vb, pa0, pa1, pa2, pa3);
; }
; DEV void attn_pass(const u16* __restrict__ Qb, const u16* __restrict__ Kh, const u16* __restrict__ Vh, int seq, f32x16* o, float* rli) {
;     ...
;     pv_d0(o, vb0 + b0 * AT_SHM_V, pa0, pa1, pa2, pa3); partialSM(pA0, pA1, m_reg, mnA, alA);
;     SWAIT(); SWRITE(b2, SO);
.LBB0_76:
	s_mul_hi_u32 s0, s50, 0xaaaaaaab
	s_lshr_b32 s0, s0, 1
	s_mul_i32 s1, s0, 0x6000
	s_mul_i32 s0, s0, 0xc000
	s_mul_i32 s12, s12, 0xc000
	v_subrev_u32_e32 v194, s1, v205
	v_subrev_u32_e32 v195, s0, v206
	v_subrev_u32_e32 v218, s0, v207
	v_subrev_u32_e32 v158, s12, v208
	v_add_u32_e32 v219, s8, v158
	ds_read_b64_tr_b16 v[158:159], v219 offset:0
	ds_read_b64_tr_b16 v[160:161], v219 offset:0x800
	ds_read_b64_tr_b16 v[164:165], v219 offset:0x1000
	ds_read_b64_tr_b16 v[166:167], v219 offset:0x1800
	ds_read_b64_tr_b16 v[186:187], v219 offset:0x2000
	ds_read_b64_tr_b16 v[188:189], v219 offset:0x2800
	ds_read_b64_tr_b16 v[190:191], v219 offset:0x3000
	ds_read_b64_tr_b16 v[192:193], v219 offset:0x3800
	s_waitcnt lgkmcnt(0)
	s_nop 0
	v_mfma_f32_32x32x16_bf16 v[0:15], v[136:139], v[158:161], v[0:15]
	ds_read_b64_tr_b16 v[158:159], v219 offset:0x200
	ds_read_b64_tr_b16 v[160:161], v219 offset:0xa00
	v_mfma_f32_32x32x16_bf16 v[0:15], v[140:143], v[164:167], v[0:15]
	ds_read_b64_tr_b16 v[164:165], v219 offset:0x1200
	ds_read_b64_tr_b16 v[166:167], v219 offset:0x1a00
	v_mfma_f32_32x32x16_bf16 v[0:15], v[144:147], v[186:189], v[0:15]
	ds_read_b64_tr_b16 v[186:187], v219 offset:0x2200
	ds_read_b64_tr_b16 v[188:189], v219 offset:0x2a00
	v_mfma_f32_32x32x16_bf16 v[0:15], v[148:151], v[190:193], v[0:15]
	ds_read_b64_tr_b16 v[190:191], v219 offset:0x3200
	ds_read_b64_tr_b16 v[192:193], v219 offset:0x3a00
	s_waitcnt lgkmcnt(0)
	v_mfma_f32_32x32x16_bf16 v[48:63], v[136:139], v[158:161], v[48:63]
	ds_read_b64_tr_b16 v[158:159], v219 offset:0x400
	ds_read_b64_tr_b16 v[160:161], v219 offset:0xc00
	v_mfma_f32_32x32x16_bf16 v[48:63], v[140:143], v[164:167], v[48:63]
	ds_read_b64_tr_b16 v[164:165], v219 offset:0x1400
	ds_read_b64_tr_b16 v[166:167], v219 offset:0x1c00
	v_mfma_f32_32x32x16_bf16 v[48:63], v[144:147], v[186:189], v[48:63]
	ds_read_b64_tr_b16 v[186:187], v219 offset:0x2400
	ds_read_b64_tr_b16 v[188:189], v219 offset:0x2c00
	v_mfma_f32_32x32x16_bf16 v[48:63], v[148:151], v[190:193], v[48:63]
	ds_read_b64_tr_b16 v[190:191], v219 offset:0x3400
	ds_read_b64_tr_b16 v[192:193], v219 offset:0x3c00
	s_waitcnt lgkmcnt(0)
	v_mfma_f32_32x32x16_bf16 v[32:47], v[136:139], v[158:161], v[32:47]
	ds_read_b64_tr_b16 v[158:159], v219 offset:0x600
	ds_read_b64_tr_b16 v[160:161], v219 offset:0xe00
	v_mfma_f32_32x32x16_bf16 v[32:47], v[140:143], v[164:167], v[32:47]
	ds_read_b64_tr_b16 v[164:165], v219 offset:0x1600
	ds_read_b64_tr_b16 v[166:167], v219 offset:0x1e00
	v_mfma_f32_32x32x16_bf16 v[32:47], v[144:147], v[186:189], v[32:47]
	ds_read_b64_tr_b16 v[186:187], v219 offset:0x2600
	ds_read_b64_tr_b16 v[188:189], v219 offset:0x2e00
	v_mfma_f32_32x32x16_bf16 v[32:47], v[148:151], v[190:193], v[32:47]
	ds_read_b64_tr_b16 v[190:191], v219 offset:0x3600
	ds_read_b64_tr_b16 v[192:193], v219 offset:0x3e00
	s_waitcnt lgkmcnt(0)
	v_mfma_f32_32x32x16_bf16 v[16:31], v[136:139], v[158:161], v[16:31]
	v_max_f32_e32 v136, v80, v81
	v_max3_f32 v136, v136, v82, v83
	v_max3_f32 v136, v136, v84, v85
	v_max3_f32 v136, v136, v86, v87
	v_max3_f32 v136, v136, v88, v89
	v_max3_f32 v136, v136, v90, v91
	v_max3_f32 v136, v136, v92, v93
	v_max3_f32 v136, v136, v94, v95
	v_mfma_f32_32x32x16_bf16 v[16:31], v[140:143], v[164:167], v[16:31]
	v_max3_f32 v136, v136, v64, v65
	v_max3_f32 v136, v136, v66, v67
	v_max3_f32 v136, v136, v68, v69
	v_max3_f32 v136, v136, v70, v71
	v_max3_f32 v136, v136, v72, v73
	v_max3_f32 v136, v136, v74, v75
	v_max3_f32 v136, v136, v76, v77
	v_max3_f32 v136, v136, v78, v79
	v_mfma_f32_32x32x16_bf16 v[16:31], v[144:147], v[186:189], v[16:31]
	v_mov_b32_e32 v137, v136
	s_nop 1
	v_permlane32_swap_b32_e32 v136, v137
	v_max_f32_e32 v136, v136, v137
	v_sub_f32_e32 v137, v136, v215
	v_cmp_ge_f32_e32 vcc, s18, v137
	v_mfma_f32_32x32x16_bf16 v[16:31], v[148:151], v[190:193], v[16:31]
	s_cmp_eq_u64 vcc, exec
	s_cselect_b64 s[0:1], -1, 0
	s_cbranch_scc1 .Lattn_fast2
	v_max_f32_e32 v136, v215, v136
	v_sub_f32_e32 v137, v215, v136
	v_mul_f32_e32 v137, 0x3e38aa3b, v137
	v_exp_f32_e32 v137, v137
.Lattn_fast2:
	s_waitcnt vmcnt(3)
	s_and_b64 vcc, exec, s[10:11]
	s_cbranch_vccz .Lattn1_pf_inflight
	s_waitcnt vmcnt(0)

; DEV void finishSM(f32x16& p0, f32x16& p1, float alpha, float& l_reg, bf16x8& pa0, bf16x8& pa1, bf16x8& pa2, bf16x8& pa3) {
; #pragma unroll
;   for (int r = 0; r < 16; ++r) p1[r] = __builtin_amdgcn_exp2f(p1[r]);
;   float ps = 0;
; #pragma unroll
;   for (int r = 0; r < 16; ++r) ps += p0[r];
; #pragma unroll
;   for (int r = 0; r < 16; ++r) ps += p1[r];
;   { auto rr = __builtin_amdgcn_permlane32_swap(__float_as_uint(ps), __float_as_uint(ps), false, false);
;     ps = __uint_as_float(rr[0]) + __uint_as_float(rr[1]); }
;   l_reg = l_reg * alpha + ps;
;     ...
;   PK4(p0, 0, pa0); PK4(p0, 8, pa1); PK4(p1, 0, pa2); PK4(p1, 8, pa3);
;     ...
; }
; DEV void qkt(f32x16& p0, f32x16& p1, const char* Ks, const bf16x8* qr, int r32, int hi) {
;   p0 = f32x16{}; p1 = f32x16{};
; #pragma unroll
;   for (int d0 = 0; d0 < 4; ++d0) { int cb = (d0 * 16 + hi * 8) * 2;
;     bf16x8 b0 = *reinterpret_cast<const bf16x8*>(Ks + KSWZ64(r32, cb));
;     bf16x8 b1 = *reinterpret_cast<const bf16x8*>(Ks + KSWZ64(32 + r32, cb));
;     p0 = __builtin_amdgcn_mfma_f32_32x32x16_bf16(b0, qr[d0], p0, 0, 0, 0);
;     p1 = __builtin_amdgcn_mfma_f32_32x32x16_bf16(b1, qr[d0], p1, 0, 0, 0); }
; }
; DEV int v_st(int k, int c) { const int kk = (k & ~0xC) | ((k & 4) << 1) | ((k & 8) >> 1); return ((kk >> 3) * 4 + (c >> 5)) * 512 + ((kk & 7) * 32 + (c & 31)) * 2; }
; DEV int v_rd_base(int lane) { return ((lane & 3) << 3) | (((lane >> 2) & 3) << 6) | (((lane >> 4) & 1) << 5) | (((lane >> 5) & 1) << 8); }
; template <int OFF> DEV s16x4 tr_read(int vb) {
;   s16x4 r; asm volatile("ds_read_b64_tr_b16 %0, %1 offset:%2" : "=&v"(r) : "v"(vb), "i"(OFF) : "memory"); return r;
; }
; template <int D0> DEV void pv_one(f32x16& od, int vb, bf16x8 pa0, bf16x8 pa1, bf16x8 pa2, bf16x8 pa3) {
;   const s16x4 l0 = tr_read<v_rd_off(D0, 0, 0)>(vb), h0 = tr_read<v_rd_off(D0, 0, 1)>(vb), l1 = tr_read<v_rd_off(D0, 1, 0)>(vb), h1 = tr_read<v_rd_off(D0, 1, 1)>(vb);
;   const s16x4 l2 = tr_read<v_rd_off(D0, 2, 0)>(vb), h2 = tr_read<v_rd_off(D0, 2, 1)>(vb), l3 = tr_read<v_rd_off(D0, 3, 0)>(vb), h3 = tr_read<v_rd_off(D0, 3, 1)>(vb);
;   asm volatile("s_waitcnt lgkmcnt(0)" ::: "memory"); SBAR();
;     ...
;   od = __builtin_amdgcn_mfma_f32_32x32x16_bf16(pa0, PK(l0, h0), od, 0, 0, 0);
;   od = __builtin_amdgcn_mfma_f32_32x32x16_bf16(pa1, PK(l1, h1), od, 0, 0, 0);
;   od = __builtin_amdgcn_mfma_f32_32x32x16_bf16(pa2, PK(l2, h2), od, 0, 0, 0);
.LBB0_82:
	s_add_i32 s0, s44, 0xffff
	s_and_b32 s1, s0, 0xff
	s_mulk_i32 s1, 0xab
	s_bfe_u32 s1, s1, 0x70009
	s_mul_i32 s1, s1, 3
	s_sub_i32 s0, s0, s1
	s_and_b32 s10, s0, 0xff
	s_add_i32 s0, s44, 0xfffe
	s_and_b32 s1, s0, 0xff
	s_mulk_i32 s1, 0xab
	s_bfe_u32 s1, s1, 0x70009
	v_or_b32_e32 v64, v176, v177
	s_mul_i32 s1, s1, 3
	v_or3_b32 v64, v64, v178, v179
	s_sub_i32 s0, s0, s1
	v_add_u32_e32 v112, 0, v64
	s_and_b32 s0, s0, 0xff
	s_lshl_b32 s1, s10, 13
	s_add_i32 s45, s1, 0
	v_add_u32_e32 v68, s45, v171
	ds_read_b128 v[64:67], v68 offset:49152
	ds_read_b128 v[68:71], v68 offset:53248
	v_add_u32_e32 v113, s45, v175
	v_exp_f32_e32 v118, v129
	v_exp_f32_e32 v119, v126
	s_waitcnt lgkmcnt(1)
	v_mfma_f32_32x32x16_bf16 v[80:95], v[64:67], v[108:111], 0
	v_exp_f32_e32 v120, v127
	v_exp_f32_e32 v121, v124
	v_exp_f32_e32 v122, v125
	s_waitcnt lgkmcnt(0)
	v_mfma_f32_32x32x16_bf16 v[64:79], v[68:71], v[108:111], 0
	ds_read_b128 v[108:111], v113 offset:49152
	ds_read_b128 v[114:117], v113 offset:53248
	v_exp_f32_e32 v113, v132
	s_waitcnt lgkmcnt(1)
	v_mfma_f32_32x32x16_bf16 v[80:95], v[108:111], v[104:107], v[80:95]
	v_add_u32_e32 v108, s45, v174
	s_waitcnt lgkmcnt(0)
	v_mfma_f32_32x32x16_bf16 v[64:79], v[114:117], v[104:107], v[64:79]
	ds_read_b128 v[104:107], v108 offset:49152
	ds_read_b128 v[108:111], v108 offset:53248
	v_exp_f32_e32 v114, v133
	v_exp_f32_e32 v115, v130
	v_exp_f32_e32 v116, v131
	v_exp_f32_e32 v117, v128
	s_waitcnt lgkmcnt(1)
	v_mfma_f32_32x32x16_bf16 v[80:95], v[104:107], v[100:103], v[80:95]
	v_add_u32_e32 v104, s45, v173
	s_waitcnt lgkmcnt(0)
	v_mfma_f32_32x32x16_bf16 v[64:79], v[108:111], v[100:103], v[64:79]
	ds_read_b128 v[100:103], v104 offset:49152
	ds_read_b128 v[104:107], v104 offset:53248
	v_exp_f32_e32 v108, v136
	v_exp_f32_e32 v109, v137
	v_exp_f32_e32 v110, v134
	v_exp_f32_e32 v111, v135
	s_waitcnt lgkmcnt(1)
	v_mfma_f32_32x32x16_bf16 v[80:95], v[100:103], v[96:99], v[80:95]
	v_cvt_pk_bf16_f32 v100, v158, v214
	v_cvt_pk_bf16_f32 v101, v159, v215
	v_cvt_pk_bf16_f32 v102, v142, v146
	v_cvt_pk_bf16_f32 v103, v143, v147
	s_waitcnt lgkmcnt(0)
	v_mfma_f32_32x32x16_bf16 v[64:79], v[104:107], v[96:99], v[64:79]
	v_add_f32_e32 v96, v160, v150
	v_add_f32_e32 v96, v151, v96
	v_add_f32_e32 v96, v161, v96
	v_add_f32_e32 v96, v158, v96
	v_add_f32_e32 v96, v214, v96
	v_add_f32_e32 v96, v159, v96
	v_add_f32_e32 v96, v215, v96
	v_add_f32_e32 v96, v142, v96
	v_add_f32_e32 v96, v146, v96
	v_add_f32_e32 v96, v143, v96
	v_add_f32_e32 v96, v147, v96
	v_exp_f32_e32 v106, v138
	v_add_f32_e32 v96, v144, v96
	v_exp_f32_e32 v107, v139
	v_add_f32_e32 v96, v148, v96
	v_add_f32_e32 v96, v145, v96
	v_add_f32_e32 v96, v149, v96
	v_add_f32_e32 v96, v106, v96
	v_add_f32_e32 v96, v107, v96
	v_add_f32_e32 v96, v108, v96
	v_add_f32_e32 v96, v109, v96
	v_add_f32_e32 v96, v110, v96
	v_add_f32_e32 v96, v111, v96
	v_add_f32_e32 v96, v113, v96
	v_add_f32_e32 v96, v114, v96
	v_add_f32_e32 v96, v115, v96
	v_add_f32_e32 v96, v116, v96
	v_add_f32_e32 v96, v117, v96
	v_add_f32_e32 v96, v118, v96
	v_add_f32_e32 v96, v119, v96
	v_add_f32_e32 v96, v120, v96
	v_add_f32_e32 v96, v121, v96
	v_add_f32_e32 v96, v122, v96
	v_mov_b32_e32 v97, v96
	v_cvt_pk_bf16_f32 v98, v150, v160
	v_cvt_pk_bf16_f32 v99, v151, v161
	s_nop 1
	v_permlane32_swap_b32_e32 v96, v97
	v_permlane32_swap_b32_e32 v98, v100
	v_permlane32_swap_b32_e32 v99, v101
	v_cvt_pk_bf16_f32 v104, v144, v148
	v_cvt_pk_bf16_f32 v105, v145, v149
	v_cvt_pk_bf16_f32 v106, v106, v107
	v_cvt_pk_bf16_f32 v107, v108, v109
	v_cvt_pk_bf16_f32 v108, v110, v111
	v_cvt_pk_bf16_f32 v109, v113, v114
	v_cvt_pk_bf16_f32 v114, v115, v116
	v_cvt_pk_bf16_f32 v115, v117, v118
	v_cvt_pk_bf16_f32 v116, v119, v120
	v_cvt_pk_bf16_f32 v117, v121, v122
	s_nop 0
	v_permlane32_swap_b32_e32 v102, v104
	v_permlane32_swap_b32_e32 v103, v105
	v_permlane32_swap_b32_e32 v106, v108
	v_permlane32_swap_b32_e32 v107, v109
	v_permlane32_swap_b32_e32 v114, v116
	v_permlane32_swap_b32_e32 v115, v117
	s_lshl_b32 s50, s0, 14
	v_add_u32_e32 v110, s50, v112
	ds_read_b64_tr_b16 v[118:119], v110 offset:0
	ds_read_b64_tr_b16 v[120:121], v110 offset:0x800
	ds_read_b64_tr_b16 v[122:123], v110 offset:0x1000
	ds_read_b64_tr_b16 v[124:125], v110 offset:0x1800
	ds_read_b64_tr_b16 v[126:127], v110 offset:0x2000
	ds_read_b64_tr_b16 v[128:129], v110 offset:0x2800
	ds_read_b64_tr_b16 v[130:131], v110 offset:0x3000
	ds_read_b64_tr_b16 v[132:133], v110 offset:0x3800
	s_waitcnt lgkmcnt(0)
	s_nop 0
	v_mfma_f32_32x32x16_bf16 v[0:15], v[98:101], v[118:121], v[0:15]
	ds_read_b64_tr_b16 v[118:119], v110 offset:0x200
	ds_read_b64_tr_b16 v[120:121], v110 offset:0xa00
	v_mfma_f32_32x32x16_bf16 v[0:15], v[102:105], v[122:125], v[0:15]
	ds_read_b64_tr_b16 v[122:123], v110 offset:0x1200
	ds_read_b64_tr_b16 v[124:125], v110 offset:0x1a00
	v_mfma_f32_32x32x16_bf16 v[0:15], v[106:109], v[126:129], v[0:15]
	ds_read_b64_tr_b16 v[126:127], v110 offset:0x2200
	ds_read_b64_tr_b16 v[128:129], v110 offset:0x2a00
	v_mfma_f32_32x32x16_bf16 v[0:15], v[114:117], v[130:133], v[0:15]
	ds_read_b64_tr_b16 v[130:131], v110 offset:0x3200
	ds_read_b64_tr_b16 v[132:133], v110 offset:0x3a00
	s_waitcnt lgkmcnt(0)
; #define RESC(a) do { if (__any((a) < 1.f)) { if (hi == 0) al_l[r32] = (a); asm volatile("s_waitcnt lgkmcnt(0)" ::: "memory"); \
;     for (int d = 0; d < 4; ++d) for (int r = 0; r < 16; ++r) o[d][r] *= al_l[crow(r, hi)]; } } while (0)
; DEV void partialSM(f32x16& p0, f32x16& p1, float& m_reg, float& mn, float& alpha) {
;   constexpr float C = AT_SCALE * 1.4426950408889634f;
;   float pmax = p0[0];
; #pragma unroll
;   for (int r = 1; r < 16; ++r) pmax = fmaxf(pmax, p0[r]);
; #pragma unroll
;   for (int r = 0; r < 16; ++r) pmax = fmaxf(pmax, p1[r]);
;   { auto rr = __builtin_amdgcn_permlane32_swap(__float_as_uint(pmax), __float_as_uint(pmax), false, false);
;     pmax = fmaxf(__uint_as_float(rr[0]), __uint_as_float(rr[1])); }
;   if (__builtin_expect(__all(pmax - m_reg <= AT_THR / AT_SCALE), 1)) { mn = m_reg; alpha = 1.f; }
;   else { mn = fmaxf(m_reg, pmax); alpha = __builtin_amdgcn_exp2f((m_reg - mn) * C); m_reg = mn; }
; DEV void attn_pass(const u16* __restrict__ Qb, const u16* __restrict__ Kh, const u16* __restrict__ Vh, int seq, f32x16* o, float* rli) {
;     ...
;     pv_d0(o, vb0 + bp * AT_SHM_V, pa0, pa1, pa2, pa3); partialSM(pB0, pB1, m_reg, mnB, alB);
;     RESC(alB);
	v_mfma_f32_32x32x16_bf16 v[48:63], v[98:101], v[118:121], v[48:63]
	ds_read_b64_tr_b16 v[118:119], v110 offset:0x400
	ds_read_b64_tr_b16 v[120:121], v110 offset:0xc00
	v_mfma_f32_32x32x16_bf16 v[48:63], v[102:105], v[122:125], v[48:63]
	ds_read_b64_tr_b16 v[122:123], v110 offset:0x1400
	ds_read_b64_tr_b16 v[124:125], v110 offset:0x1c00
	v_mfma_f32_32x32x16_bf16 v[48:63], v[106:109], v[126:129], v[48:63]
	ds_read_b64_tr_b16 v[126:127], v110 offset:0x2400
	ds_read_b64_tr_b16 v[128:129], v110 offset:0x2c00
	v_mfma_f32_32x32x16_bf16 v[48:63], v[114:117], v[130:133], v[48:63]
	ds_read_b64_tr_b16 v[130:131], v110 offset:0x3400
	ds_read_b64_tr_b16 v[132:133], v110 offset:0x3c00
	s_waitcnt lgkmcnt(0)
	v_mfma_f32_32x32x16_bf16 v[32:47], v[98:101], v[118:121], v[32:47]
	ds_read_b64_tr_b16 v[118:119], v110 offset:0x600
	ds_read_b64_tr_b16 v[120:121], v110 offset:0xe00
	v_mfma_f32_32x32x16_bf16 v[32:47], v[102:105], v[122:125], v[32:47]
	ds_read_b64_tr_b16 v[122:123], v110 offset:0x1600
	ds_read_b64_tr_b16 v[124:125], v110 offset:0x1e00
	v_mfma_f32_32x32x16_bf16 v[32:47], v[106:109], v[126:129], v[32:47]
	ds_read_b64_tr_b16 v[126:127], v110 offset:0x2600
	ds_read_b64_tr_b16 v[128:129], v110 offset:0x2e00
	v_mfma_f32_32x32x16_bf16 v[32:47], v[114:117], v[130:133], v[32:47]
	ds_read_b64_tr_b16 v[130:131], v110 offset:0x3600
	ds_read_b64_tr_b16 v[132:133], v110 offset:0x3e00
	s_waitcnt lgkmcnt(0)
	v_mfma_f32_32x32x16_bf16 v[16:31], v[98:101], v[118:121], v[16:31]
	v_max_f32_e32 v98, v81, v81
	v_max_f32_e32 v99, v80, v80
	v_max_f32_e32 v98, v99, v98
	v_max3_f32 v98, v98, v82, v83
	v_max3_f32 v98, v98, v84, v85
	v_max3_f32 v98, v98, v86, v87
	v_max3_f32 v98, v98, v88, v89
	v_max3_f32 v98, v98, v90, v91
	v_max3_f32 v98, v98, v92, v93
	v_mfma_f32_32x32x16_bf16 v[16:31], v[102:105], v[122:125], v[16:31]
	v_max3_f32 v98, v98, v94, v95
	v_max3_f32 v98, v98, v64, v65
	v_max3_f32 v98, v98, v66, v67
	v_max3_f32 v98, v98, v68, v69
	v_max3_f32 v98, v98, v70, v71
	v_max3_f32 v98, v98, v72, v73
	v_max3_f32 v98, v98, v74, v75
	v_max3_f32 v98, v98, v76, v77
	v_mfma_f32_32x32x16_bf16 v[16:31], v[106:109], v[126:129], v[16:31]
	v_max3_f32 v98, v98, v78, v79
	v_mov_b32_e32 v99, v98
	s_nop 1
	v_permlane32_swap_b32_e32 v98, v99
	v_max_f32_e32 v99, v99, v99
	v_max_f32_e32 v98, v98, v98
	v_max_f32_e32 v98, v98, v99
	v_sub_f32_e32 v99, v98, v140
	v_cmp_ge_f32_e32 vcc, s18, v99
	v_max_f32_e32 v99, v140, v140
	v_max_f32_e32 v99, v99, v98
	v_mfma_f32_32x32x16_bf16 v[16:31], v[114:117], v[130:133], v[16:31]
	v_sub_f32_e32 v98, v140, v99
	v_mul_f32_e32 v98, 0x3e38aa3b, v98
	v_exp_f32_e32 v98, v98
	s_cmp_eq_u64 vcc, exec
	s_cselect_b64 s[0:1], -1, 0
	v_cndmask_b32_e64 v98, v98, 1.0, s[0:1]
	v_cmp_gt_f32_e32 vcc, 1.0, v98
	s_cbranch_vccz .LBB0_86
	s_and_saveexec_b64 s[8:9], s[6:7]
	s_mov_b32 s66, 0x800000
	ds_write_b32 v169, v98 offset:128
	s_or_b64 exec, exec, s[8:9]
	s_waitcnt lgkmcnt(0)
	v_add_u32_e32 v113, v168, v162
	ds_read_b128 v[100:103], v113 offset:224
	ds_read_b128 v[104:107], v113 offset:192
	ds_read_b128 v[108:111], v113 offset:160
	ds_read_b128 v[114:117], v113 offset:128
	s_waitcnt lgkmcnt(3)
	v_pk_mul_f32 v[12:13], v[12:13], v[100:101]
	s_waitcnt lgkmcnt(2)
	v_pk_mul_f32 v[8:9], v[8:9], v[104:105]
	s_waitcnt lgkmcnt(1)
	v_pk_mul_f32 v[4:5], v[4:5], v[108:109]
	v_pk_mul_f32 v[14:15], v[14:15], v[102:103]
	v_pk_mul_f32 v[10:11], v[10:11], v[106:107]
	v_pk_mul_f32 v[6:7], v[6:7], v[110:111]
	s_waitcnt lgkmcnt(0)
	v_pk_mul_f32 v[2:3], v[2:3], v[116:117]
	v_pk_mul_f32 v[0:1], v[0:1], v[114:115]
	v_pk_mul_f32 v[60:61], v[60:61], v[100:101]
	v_pk_mul_f32 v[56:57], v[56:57], v[104:105]
	v_pk_mul_f32 v[52:53], v[52:53], v[108:109]
	v_pk_mul_f32 v[62:63], v[62:63], v[102:103]
	v_pk_mul_f32 v[58:59], v[58:59], v[106:107]
	v_pk_mul_f32 v[54:55], v[54:55], v[110:111]
	v_pk_mul_f32 v[50:51], v[50:51], v[116:117]
	v_pk_mul_f32 v[48:49], v[48:49], v[114:115]
	v_pk_mul_f32 v[44:45], v[44:45], v[100:101]
	v_pk_mul_f32 v[40:41], v[40:41], v[104:105]
	v_pk_mul_f32 v[36:37], v[36:37], v[108:109]
	v_pk_mul_f32 v[46:47], v[46:47], v[102:103]
	v_pk_mul_f32 v[42:43], v[42:43], v[106:107]
	v_pk_mul_f32 v[38:39], v[38:39], v[110:111]
	v_pk_mul_f32 v[34:35], v[34:35], v[116:117]
	v_pk_mul_f32 v[32:33], v[32:33], v[114:115]
	v_pk_mul_f32 v[28:29], v[28:29], v[100:101]
	v_pk_mul_f32 v[24:25], v[24:25], v[104:105]
	v_pk_mul_f32 v[20:21], v[20:21], v[108:109]
	v_pk_mul_f32 v[30:31], v[30:31], v[102:103]
	v_pk_mul_f32 v[26:27], v[26:27], v[106:107]
	v_pk_mul_f32 v[22:23], v[22:23], v[110:111]
	v_pk_mul_f32 v[18:19], v[18:19], v[116:117]
	v_pk_mul_f32 v[16:17], v[16:17], v[114:115]
	s_branch .LBB0_87

; DEV void partialSM(f32x16& p0, f32x16& p1, float& m_reg, float& mn, float& alpha) {
;     ...
;   float mnC = -mn * C;
; #pragma unroll
;   for (int r = 0; r < 16; ++r) p0[r] = fmaf(p0[r], C, mnC);
; #pragma unroll
;   for (int r = 0; r < 16; ++r) p1[r] = fmaf(p1[r], C, mnC);
; #pragma unroll
;   for (int r = 0; r < 16; ++r) p0[r] = __builtin_amdgcn_exp2f(p0[r]);
; }
; DEV void finishSM(f32x16& p0, f32x16& p1, float alpha, float& l_reg, bf16x8& pa0, bf16x8& pa1, bf16x8& pa2, bf16x8& pa3) {
; #pragma unroll
;   for (int r = 0; r < 16; ++r) p1[r] = __builtin_amdgcn_exp2f(p1[r]);
;   float ps = 0;
; #pragma unroll
;   for (int r = 0; r < 16; ++r) ps += p0[r];
; #pragma unroll
;   for (int r = 0; r < 16; ++r) ps += p1[r];
;   { auto rr = __builtin_amdgcn_permlane32_swap(__float_as_uint(ps), __float_as_uint(ps), false, false);
;     ps = __uint_as_float(rr[0]) + __uint_as_float(rr[1]); }
;   l_reg = l_reg * alpha + ps;
;     ...
;   PK4(p0, 0, pa0); PK4(p0, 8, pa1); PK4(p1, 0, pa2); PK4(p1, 8, pa3);
;     ...
; }
; DEV void qkt(f32x16& p0, f32x16& p1, const char* Ks, const bf16x8* qr, int r32, int hi) {
;   p0 = f32x16{}; p1 = f32x16{};
; #pragma unroll
;   for (int d0 = 0; d0 < 4; ++d0) { int cb = (d0 * 16 + hi * 8) * 2;
;     bf16x8 b0 = *reinterpret_cast<const bf16x8*>(Ks + KSWZ64(r32, cb));
;     bf16x8 b1 = *reinterpret_cast<const bf16x8*>(Ks + KSWZ64(32 + r32, cb));
;     p0 = __builtin_amdgcn_mfma_f32_32x32x16_bf16(b0, qr[d0], p0, 0, 0, 0);
;     p1 = __builtin_amdgcn_mfma_f32_32x32x16_bf16(b1, qr[d0], p1, 0, 0, 0); }
; }
; DEV int v_st(int k, int c) { const int kk = (k & ~0xC) | ((k & 4) << 1) | ((k & 8) >> 1); return ((kk >> 3) * 4 + (c >> 5)) * 512 + ((kk & 7) * 32 + (c & 31)) * 2; }
; DEV int v_rd_base(int lane) { return ((lane & 3) << 3) | (((lane >> 2) & 3) << 6) | (((lane >> 4) & 1) << 5) | (((lane >> 5) & 1) << 8); }
; template <int OFF> DEV s16x4 tr_read(int vb) {
;   s16x4 r; asm volatile("ds_read_b64_tr_b16 %0, %1 offset:%2" : "=&v"(r) : "v"(vb), "i"(OFF) : "memory"); return r;
; }
; template <int D0> DEV void pv_one(f32x16& od, int vb, bf16x8 pa0, bf16x8 pa1, bf16x8 pa2, bf16x8 pa3) {
;   const s16x4 l0 = tr_read<v_rd_off(D0, 0, 0)>(vb), h0 = tr_read<v_rd_off(D0, 0, 1)>(vb), l1 = tr_read<v_rd_off(D0, 1, 0)>(vb), h1 = tr_read<v_rd_off(D0, 1, 1)>(vb);
.LBB0_87:
	v_cndmask_b32_e64 v99, v99, v140, s[0:1]
	v_mul_f32_e32 v99, 0xbe38aa3b, v99
	v_fmamk_f32 v80, v80, 0x3e38aa3b, v99
	v_fmamk_f32 v81, v81, 0x3e38aa3b, v99
	v_fmamk_f32 v82, v82, 0x3e38aa3b, v99
	v_fmamk_f32 v83, v83, 0x3e38aa3b, v99
	v_fmamk_f32 v84, v84, 0x3e38aa3b, v99
	v_fmamk_f32 v85, v85, 0x3e38aa3b, v99
	v_fmamk_f32 v86, v86, 0x3e38aa3b, v99
	v_fmamk_f32 v87, v87, 0x3e38aa3b, v99
	v_fmamk_f32 v88, v88, 0x3e38aa3b, v99
	v_fmamk_f32 v89, v89, 0x3e38aa3b, v99
	v_fmamk_f32 v90, v90, 0x3e38aa3b, v99
	v_fmamk_f32 v91, v91, 0x3e38aa3b, v99
	v_fmamk_f32 v92, v92, 0x3e38aa3b, v99
	v_fmamk_f32 v93, v93, 0x3e38aa3b, v99
	v_fmamk_f32 v94, v94, 0x3e38aa3b, v99
	v_fmamk_f32 v95, v95, 0x3e38aa3b, v99
	v_fmamk_f32 v64, v64, 0x3e38aa3b, v99
	v_fmamk_f32 v65, v65, 0x3e38aa3b, v99
	v_fmamk_f32 v66, v66, 0x3e38aa3b, v99
	v_fmamk_f32 v67, v67, 0x3e38aa3b, v99
	v_fmamk_f32 v68, v68, 0x3e38aa3b, v99
	v_fmamk_f32 v69, v69, 0x3e38aa3b, v99
	v_fmamk_f32 v70, v70, 0x3e38aa3b, v99
	v_fmamk_f32 v71, v71, 0x3e38aa3b, v99
	v_fmamk_f32 v72, v72, 0x3e38aa3b, v99
	v_fmamk_f32 v73, v73, 0x3e38aa3b, v99
	v_fmamk_f32 v74, v74, 0x3e38aa3b, v99
	v_fmamk_f32 v75, v75, 0x3e38aa3b, v99
	v_fmamk_f32 v76, v76, 0x3e38aa3b, v99
	v_fmamk_f32 v77, v77, 0x3e38aa3b, v99
	v_fmamk_f32 v78, v78, 0x3e38aa3b, v99
	v_fmac_f32_e32 v99, 0x3e38aa3b, v79
	v_exp_f32_e32 v79, v80
	v_exp_f32_e32 v80, v81
	v_exp_f32_e32 v81, v82
	v_exp_f32_e32 v82, v83
	v_exp_f32_e32 v83, v84
	v_exp_f32_e32 v84, v85
	v_exp_f32_e32 v85, v86
	v_exp_f32_e32 v86, v87
	v_exp_f32_e32 v87, v88
	v_exp_f32_e32 v88, v89
	v_exp_f32_e32 v89, v90
	v_exp_f32_e32 v90, v91
	v_exp_f32_e32 v91, v92
	v_exp_f32_e32 v92, v93
	v_exp_f32_e32 v93, v94
	v_exp_f32_e32 v94, v95
	v_exp_f32_e32 v95, v64
	v_add_f32_e32 v64, v80, v79
	v_add_f32_e32 v64, v81, v64
	v_add_f32_e32 v64, v82, v64
	v_add_f32_e32 v64, v83, v64
	v_add_f32_e32 v64, v84, v64
	v_add_f32_e32 v64, v85, v64
	v_add_f32_e32 v64, v86, v64
	v_add_f32_e32 v64, v87, v64
	v_add_f32_e32 v64, v88, v64
	v_add_f32_e32 v64, v89, v64
	v_add_f32_e32 v64, v90, v64
	v_add_f32_e32 v64, v91, v64
	v_exp_f32_e32 v100, v65
	v_add_f32_e32 v64, v92, v64
	v_exp_f32_e32 v101, v66
	v_add_f32_e32 v64, v93, v64
	v_exp_f32_e32 v102, v67
	v_add_f32_e32 v64, v94, v64
	v_exp_f32_e32 v103, v68
	v_add_f32_e32 v64, v95, v64
	v_exp_f32_e32 v104, v69
	v_add_f32_e32 v64, v100, v64
	v_exp_f32_e32 v105, v70
	v_add_f32_e32 v64, v101, v64
	v_exp_f32_e32 v106, v71
	v_add_f32_e32 v64, v102, v64
	v_exp_f32_e32 v107, v72
	v_add_f32_e32 v64, v103, v64
	v_exp_f32_e32 v108, v73
	v_add_f32_e32 v64, v104, v64
	v_exp_f32_e32 v109, v74
	v_add_f32_e32 v64, v105, v64
	v_exp_f32_e32 v110, v75
	v_add_f32_e32 v64, v106, v64
	v_exp_f32_e32 v111, v76
	v_add_f32_e32 v64, v107, v64
	v_exp_f32_e32 v113, v77
	v_add_f32_e32 v64, v108, v64
	v_exp_f32_e32 v114, v78
	v_add_f32_e32 v64, v109, v64
	v_exp_f32_e32 v99, v99
	v_add_f32_e32 v64, v110, v64
	v_add_f32_e32 v64, v111, v64
	v_add_f32_e32 v64, v113, v64
	v_add_f32_e32 v64, v114, v64
	v_add_f32_e32 v64, v99, v64
	v_mov_b32_e32 v65, v64
	s_nop 1
	v_permlane32_swap_b32_e32 v64, v65
	v_cvt_pk_bf16_f32 v66, v79, v80
	v_cvt_pk_bf16_f32 v67, v81, v82
	v_cvt_pk_bf16_f32 v68, v83, v84
	v_cvt_pk_bf16_f32 v69, v85, v86
	v_cvt_pk_bf16_f32 v70, v87, v88
	v_cvt_pk_bf16_f32 v71, v89, v90
	v_cvt_pk_bf16_f32 v72, v91, v92
	v_cvt_pk_bf16_f32 v73, v93, v94
	v_cvt_pk_bf16_f32 v74, v95, v100
	v_cvt_pk_bf16_f32 v75, v101, v102
	v_cvt_pk_bf16_f32 v76, v103, v104
	v_cvt_pk_bf16_f32 v77, v105, v106
	v_cvt_pk_bf16_f32 v78, v107, v108
	v_cvt_pk_bf16_f32 v79, v109, v110
	v_cvt_pk_bf16_f32 v80, v111, v113
	v_cvt_pk_bf16_f32 v81, v114, v99
	s_nop 0
	v_permlane32_swap_b32_e32 v66, v68
	v_permlane32_swap_b32_e32 v67, v69
	v_permlane32_swap_b32_e32 v70, v72
	v_permlane32_swap_b32_e32 v71, v73
	v_permlane32_swap_b32_e32 v74, v76
	v_permlane32_swap_b32_e32 v75, v77
	v_permlane32_swap_b32_e32 v78, v80
	v_permlane32_swap_b32_e32 v79, v81
	s_lshl_b32 s51, s10, 14
	v_add_u32_e32 v94, s51, v112
	ds_read_b64_tr_b16 v[82:83], v94 offset:0
	ds_read_b64_tr_b16 v[84:85], v94 offset:0x800
	ds_read_b64_tr_b16 v[86:87], v94 offset:0x1000
	ds_read_b64_tr_b16 v[88:89], v94 offset:0x1800
	ds_read_b64_tr_b16 v[90:91], v94 offset:0x2000
	ds_read_b64_tr_b16 v[92:93], v94 offset:0x2800
	ds_read_b64_tr_b16 v[100:101], v94 offset:0x3000
	ds_read_b64_tr_b16 v[102:103], v94 offset:0x3800
	s_waitcnt lgkmcnt(0)
	s_nop 0
	v_mfma_f32_32x32x16_bf16 v[0:15], v[66:69], v[82:85], v[0:15]
	ds_read_b64_tr_b16 v[82:83], v94 offset:0x200
	ds_read_b64_tr_b16 v[84:85], v94 offset:0xa00
	v_mfma_f32_32x32x16_bf16 v[0:15], v[70:73], v[86:89], v[0:15]
	ds_read_b64_tr_b16 v[86:87], v94 offset:0x1200
	ds_read_b64_tr_b16 v[88:89], v94 offset:0x1a00
	v_mfma_f32_32x32x16_bf16 v[0:15], v[74:77], v[90:93], v[0:15]
	ds_read_b64_tr_b16 v[90:91], v94 offset:0x2200
	ds_read_b64_tr_b16 v[92:93], v94 offset:0x2a00
	v_mfma_f32_32x32x16_bf16 v[0:15], v[78:81], v[100:103], v[0:15]
	ds_read_b64_tr_b16 v[100:101], v94 offset:0x3200
	ds_read_b64_tr_b16 v[102:103], v94 offset:0x3a00
	s_waitcnt lgkmcnt(0)
	v_mfma_f32_32x32x16_bf16 v[48:63], v[66:69], v[82:85], v[48:63]
	ds_read_b64_tr_b16 v[82:83], v94 offset:0x400
	ds_read_b64_tr_b16 v[84:85], v94 offset:0xc00
	v_mfma_f32_32x32x16_bf16 v[48:63], v[70:73], v[86:89], v[48:63]
	ds_read_b64_tr_b16 v[86:87], v94 offset:0x1400
	ds_read_b64_tr_b16 v[88:89], v94 offset:0x1c00
	v_mfma_f32_32x32x16_bf16 v[48:63], v[74:77], v[90:93], v[48:63]
	ds_read_b64_tr_b16 v[90:91], v94 offset:0x2400
	ds_read_b64_tr_b16 v[92:93], v94 offset:0x2c00
	v_mfma_f32_32x32x16_bf16 v[48:63], v[78:81], v[100:103], v[48:63]
	ds_read_b64_tr_b16 v[100:101], v94 offset:0x3400
	ds_read_b64_tr_b16 v[102:103], v94 offset:0x3c00
	s_waitcnt lgkmcnt(0)
; DEV int crow(int r, int hi) { return (r & 3) + 8 * (r >> 2) + 4 * hi; }
; DEV void attn_pass(const u16* __restrict__ Qb, const u16* __restrict__ Kh, const u16* __restrict__ Vh, int seq, f32x16* o, float* rli) {
;     ...
;   if (hi == 0) li_l[r32] = l_reg; asm volatile("s_waitcnt lgkmcnt(0)" ::: "memory");
; #pragma unroll
;   for (int r = 0; r < 16; ++r) rli[r] = __builtin_amdgcn_rcpf(li_l[crow(r, hi)]);
;   __syncthreads();
; DEV void attn_item(const Params& p, int l, int b, int h, int qb, int dry) {
;     ...
;     int lz = 0; asm volatile("" : "+v"(lz));
;     float* sp = scr + (wid * 64) * 64 + lane + lz;
; #pragma unroll
;     for (int d0 = 0; d0 < 4; ++d0)
; #pragma unroll
;       for (int r = 0; r < 16; ++r) sp[(d0 * 16 + r) * 64] = o[d0][r] * rli[r];
	v_mfma_f32_32x32x16_bf16 v[32:47], v[66:69], v[82:85], v[32:47]
	ds_read_b64_tr_b16 v[82:83], v94 offset:0x600
	ds_read_b64_tr_b16 v[84:85], v94 offset:0xe00
	v_mfma_f32_32x32x16_bf16 v[32:47], v[70:73], v[86:89], v[32:47]
	ds_read_b64_tr_b16 v[86:87], v94 offset:0x1600
	ds_read_b64_tr_b16 v[88:89], v94 offset:0x1e00
	v_mfma_f32_32x32x16_bf16 v[32:47], v[74:77], v[90:93], v[32:47]
	ds_read_b64_tr_b16 v[90:91], v94 offset:0x2600
	ds_read_b64_tr_b16 v[92:93], v94 offset:0x2e00
	v_mfma_f32_32x32x16_bf16 v[32:47], v[78:81], v[100:103], v[32:47]
	ds_read_b64_tr_b16 v[100:101], v94 offset:0x3600
	ds_read_b64_tr_b16 v[102:103], v94 offset:0x3e00
	s_waitcnt lgkmcnt(0)
	v_mfma_f32_32x32x16_bf16 v[16:31], v[66:69], v[82:85], v[16:31]
	v_mfma_f32_32x32x16_bf16 v[16:31], v[70:73], v[86:89], v[16:31]
	v_mfma_f32_32x32x16_bf16 v[16:31], v[74:77], v[90:93], v[16:31]
	v_mfma_f32_32x32x16_bf16 v[16:31], v[78:81], v[100:103], v[16:31]
	s_and_saveexec_b64 s[0:1], s[6:7]
	v_add_f32_e32 v66, v96, v97
	v_fmac_f32_e32 v66, v170, v141
	v_add_f32_e32 v64, v64, v65
	v_fmac_f32_e32 v64, v66, v98
	ds_write_b32 v169, v64
	s_or_b64 exec, exec, s[0:1]
	s_waitcnt lgkmcnt(0)
	v_add_u32_e32 v72, v168, v162
	ds_read_b128 v[64:67], v72
	ds_read_b128 v[68:71], v72 offset:32
	v_and_b32_e32 v73, 63, v172
	v_lshlrev_b32_e32 v162, 2, v73
	s_movk_i32 s8, 0x2000
	s_waitcnt lgkmcnt(1)
	v_rcp_f32_e32 v74, v64
	v_rcp_f32_e32 v75, v65
	v_rcp_f32_e32 v76, v66
	v_rcp_f32_e32 v77, v67
	ds_read_b128 v[64:67], v72 offset:64
	s_waitcnt lgkmcnt(1)
	v_rcp_f32_e32 v78, v68
	v_rcp_f32_e32 v79, v69
	v_rcp_f32_e32 v80, v70
	v_rcp_f32_e32 v81, v71
	ds_read_b128 v[68:71], v72 offset:96
	s_waitcnt lgkmcnt(1)
	v_rcp_f32_e32 v82, v65
	v_lshlrev_b32_e32 v65, 6, v172
	v_rcp_f32_e32 v83, v66
	v_and_b32_e32 v66, 0xfffff000, v65
	v_rcp_f32_e32 v84, v67
	v_ashrrev_i32_e32 v67, 31, v66
	v_rcp_f32_e32 v72, v64
	v_mov_b32_e32 v64, v163
	v_lshl_add_u64 v[66:67], v[66:67], 2, s[56:57]
	s_waitcnt lgkmcnt(0)
	s_barrier
	v_lshl_add_u64 v[154:155], v[66:67], 0, v[162:163]
	v_ashrrev_i32_e32 v65, 31, v64
	v_lshl_add_u64 v[64:65], v[64:65], 2, v[154:155]
	v_mul_f32_e32 v0, v0, v74
	global_store_dword v[64:65], v0, off
	v_mul_f32_e32 v0, v1, v75
	global_store_dword v[64:65], v0, off offset:256
	v_mul_f32_e32 v0, v2, v76
	global_store_dword v[64:65], v0, off offset:512
	v_mul_f32_e32 v0, v3, v77
	global_store_dword v[64:65], v0, off offset:768
	v_mul_f32_e32 v0, v4, v78
	global_store_dword v[64:65], v0, off offset:1024
	v_mul_f32_e32 v0, v5, v79
	global_store_dword v[64:65], v0, off offset:1280
	v_mul_f32_e32 v0, v6, v80
	global_store_dword v[64:65], v0, off offset:1536
	v_mul_f32_e32 v0, v7, v81
	v_rcp_f32_e32 v68, v68
	global_store_dword v[64:65], v0, off offset:1792
	v_mul_f32_e32 v0, v8, v72
	v_rcp_f32_e32 v69, v69
	global_store_dword v[64:65], v0, off offset:2048
	v_mul_f32_e32 v0, v9, v82
	v_rcp_f32_e32 v70, v70
	global_store_dword v[64:65], v0, off offset:2304
	v_mul_f32_e32 v0, v10, v83
	v_rcp_f32_e32 v71, v71
	global_store_dword v[64:65], v0, off offset:2560
	v_mul_f32_e32 v0, v11, v84
	global_store_dword v[64:65], v0, off offset:2816
	v_mul_f32_e32 v0, v12, v68
	global_store_dword v[64:65], v0, off offset:3072
	v_mul_f32_e32 v0, v13, v69
	global_store_dword v[64:65], v0, off offset:3328
	v_mul_f32_e32 v0, v14, v70
	global_store_dword v[64:65], v0, off offset:3584
	v_mul_f32_e32 v0, v15, v71
	global_store_dword v[64:65], v0, off offset:3840
	v_add_co_u32_e32 v0, vcc, s87, v64
	v_mul_f32_e32 v4, v48, v74
	s_nop 0
	v_addc_co_u32_e32 v1, vcc, 0, v65, vcc
	v_add_co_u32_e32 v2, vcc, s8, v64
	s_or_b32 s6, s47, 1
	s_nop 0
	v_addc_co_u32_e32 v3, vcc, 0, v65, vcc
	global_store_dword v[2:3], v4, off offset:-4096
	v_mul_f32_e32 v4, v49, v75
	global_store_dword v[0:1], v4, off offset:256
	v_mul_f32_e32 v4, v50, v76
	global_store_dword v[0:1], v4, off offset:512
	v_mul_f32_e32 v4, v51, v77
	global_store_dword v[0:1], v4, off offset:768
	v_mul_f32_e32 v4, v52, v78
	global_store_dword v[0:1], v4, off offset:1024
	v_mul_f32_e32 v4, v53, v79
	global_store_dword v[0:1], v4, off offset:1280
	v_mul_f32_e32 v4, v54, v80
	global_store_dword v[0:1], v4, off offset:1536
	v_mul_f32_e32 v4, v55, v81
	global_store_dword v[0:1], v4, off offset:1792
	v_mul_f32_e32 v4, v56, v72
	global_store_dword v[0:1], v4, off offset:2048
	v_mul_f32_e32 v4, v57, v82
	global_store_dword v[0:1], v4, off offset:2304
	v_mul_f32_e32 v4, v58, v83
	global_store_dword v[0:1], v4, off offset:2560
	v_mul_f32_e32 v4, v59, v84
	global_store_dword v[0:1], v4, off offset:2816
	v_mul_f32_e32 v4, v60, v68
	global_store_dword v[0:1], v4, off offset:3072
	v_mul_f32_e32 v4, v61, v69
	global_store_dword v[0:1], v4, off offset:3328
	v_mul_f32_e32 v4, v62, v70
	global_store_dword v[0:1], v4, off offset:3584
	v_mul_f32_e32 v4, v63, v71
	global_store_dword v[0:1], v4, off offset:3840
	v_mul_f32_e32 v0, v32, v74
	global_store_dword v[2:3], v0, off
	v_mul_f32_e32 v0, v33, v75
	global_store_dword v[2:3], v0, off offset:256
	v_mul_f32_e32 v0, v34, v76
	global_store_dword v[2:3], v0, off offset:512
	v_mul_f32_e32 v0, v35, v77
	global_store_dword v[2:3], v0, off offset:768
	v_mul_f32_e32 v0, v36, v78
	global_store_dword v[2:3], v0, off offset:1024
	v_mul_f32_e32 v0, v37, v79
	global_store_dword v[2:3], v0, off offset:1280
	v_mul_f32_e32 v0, v38, v80
	global_store_dword v[2:3], v0, off offset:1536
	v_mul_f32_e32 v0, v39, v81
	global_store_dword v[2:3], v0, off offset:1792
	v_mul_f32_e32 v0, v40, v72
	global_store_dword v[2:3], v0, off offset:2048
	v_mul_f32_e32 v0, v41, v82
	global_store_dword v[2:3], v0, off offset:2304
	v_mul_f32_e32 v0, v42, v83
	global_store_dword v[2:3], v0, off offset:2560
; DEV int ltid() { int t = threadIdx.x; asm volatile("" : "+v"(t)); return t; }
; DEV int v_st(int k, int c) { const int kk = (k & ~0xC) | ((k & 4) << 1) | ((k & 8) >> 1); return ((kk >> 3) * 4 + (c >> 5)) * 512 + ((kk & 7) * 32 + (c & 31)) * 2; }
; DEV int v_rd_base(int lane) { return ((lane & 3) << 3) | (((lane >> 2) & 3) << 6) | (((lane >> 4) & 1) << 5) | (((lane >> 5) & 1) << 8); }
; #define SLOAD(i, k0) do { sr_[i].vs0 = *reinterpret_cast<const bf16x8*>(&Vh[(size_t)((k0) + sr) * 128 + sc]); sr_[i].vs1 = *reinterpret_cast<const bf16x8*>(&Vh[(size_t)((k0) + 32 + sr) * 128 + sc]); \
;     sr_[i].ks0 = *reinterpret_cast<const bf16x8*>(&Kh[(size_t)((k0) + kr) * 64 + kc]); } while (0)
; #define SWRITE(b, i) do { *(bf16x8*)(V_lds + (b) * AT_SHM_V + vst0) = sr_[i].vs0; *(bf16x8*)(V_lds + (b) * AT_SHM_V + vst1) = sr_[i].vs1; \
;     *(bf16x8*)(K_lds + (b) * AT_SHM_K + kst) = sr_[i].ks0; } while (0)
; DEV void attn_pass(const u16* __restrict__ Qb, const u16* __restrict__ Kh, const u16* __restrict__ Vh, int seq, f32x16* o, float* rli) {
;   char* lds = g_shm;
;   const int tid = ltid(), wid = tid >> 6, lane = tid & 63, r32 = lane & 31, hi = lane >> 5;
;   char* V_lds = lds; char* K_lds = lds + 3 * AT_SHM_V;
;   float* wsx = (float*)(lds + 3 * AT_SHM_V + 3 * AT_SHM_K) + wid * 64; float* li_l = wsx; float* al_l = wsx + 32;
;   float m_reg = -1e30f, l_reg = 0; bf16x8 qr[4];
; #pragma unroll
;   for (int d = 0; d < 4; ++d) o[d] = f32x16{};
;   const u16* Qw = Qb + (size_t)(wid * 32 + r32) * 64 + hi * 8;
; #pragma unroll
;   for (int d0 = 0; d0 < 4; ++d0) qr[d0] = *reinterpret_cast<const bf16x8*>(Qw + d0 * 16);
;   const int sr = tid >> 4, sc = (tid & 15) * 8, vst0 = v_st(sr, sc), vst1 = v_st(32 + sr, sc);
;   const int kr = tid >> 3, kc = (tid & 7) * 8, kst = KSWZ64(kr, kc * 2);
;   const int vb0 = (int)(uintptr_t)(__attribute__((address_space(3))) char*)V_lds + v_rd_base(lane);
;   struct { bf16x8 vs0, vs1, ks0; } sr_[2];
;     ...
;   f32x16 pA0, pA1, pB0, pB1; float mnA, mnB, alA, alB; bf16x8 pa0, pa1, pa2, pa3; const int NT = seq / 64;
;   constexpr int SE = 0, SO = 1;
;   SLOAD(SE, 0); SLOAD(SO, 64);
;   asm volatile("s_waitcnt vmcnt(3)" ::: "memory"); SWRITE(0, SE); __syncthreads();
	v_mul_f32_e32 v0, v43, v84
	global_store_dword v[2:3], v0, off offset:2816
	v_mul_f32_e32 v0, v44, v68
	global_store_dword v[2:3], v0, off offset:3072
	v_mul_f32_e32 v0, v45, v69
	global_store_dword v[2:3], v0, off offset:3328
	v_mul_f32_e32 v0, v46, v70
	global_store_dword v[2:3], v0, off offset:3584
	v_mul_f32_e32 v0, v47, v71
	global_store_dword v[2:3], v0, off offset:3840
	v_add_co_u32_e32 v0, vcc, s80, v64
	v_mul_f32_e32 v2, v16, v74
	s_nop 0
	v_addc_co_u32_e32 v1, vcc, 0, v65, vcc
	global_store_dword v[0:1], v2, off
	v_mul_f32_e32 v2, v17, v75
	global_store_dword v[0:1], v2, off offset:256
	v_mul_f32_e32 v2, v18, v76
	global_store_dword v[0:1], v2, off offset:512
	v_mul_f32_e32 v2, v19, v77
	global_store_dword v[0:1], v2, off offset:768
	v_mul_f32_e32 v2, v20, v78
	global_store_dword v[0:1], v2, off offset:1024
	v_mul_f32_e32 v2, v21, v79
	global_store_dword v[0:1], v2, off offset:1280
	v_mul_f32_e32 v2, v22, v80
	global_store_dword v[0:1], v2, off offset:1536
	v_mul_f32_e32 v2, v23, v81
	global_store_dword v[0:1], v2, off offset:1792
	v_mul_f32_e32 v2, v24, v72
	global_store_dword v[0:1], v2, off offset:2048
	v_mul_f32_e32 v2, v25, v82
	global_store_dword v[0:1], v2, off offset:2304
	v_mul_f32_e32 v2, v26, v83
	global_store_dword v[0:1], v2, off offset:2560
	v_mul_f32_e32 v2, v27, v84
	global_store_dword v[0:1], v2, off offset:2816
	v_mul_f32_e32 v2, v28, v68
	global_store_dword v[0:1], v2, off offset:3072
	v_mul_f32_e32 v2, v29, v69
	global_store_dword v[0:1], v2, off offset:3328
	v_mul_f32_e32 v2, v30, v70
	s_mul_i32 s0, s6, 0x1100
	global_store_dword v[0:1], v2, off offset:3584
	v_mul_f32_e32 v2, v31, v71
	s_mul_hi_i32 s1, s6, 0x1100
	s_add_u32 s0, s0, s46
	v_mov_b32_e32 v70, v252
	global_store_dword v[0:1], v2, off offset:3840
	s_addc_u32 s1, s1, 0
	s_lshl_b64 s[0:1], s[0:1], 7
	v_ashrrev_i32_e32 v48, 4, v70
	v_lshlrev_b32_e32 v20, 3, v70
	v_ashrrev_i32_e32 v49, 31, v48
	s_add_u32 s0, s36, s0
	v_and_b32_e32 v2, 0x78, v20
	v_add_u32_e32 v12, 32, v48
	v_lshlrev_b64 v[50:51], 8, v[48:49]
	s_addc_u32 s1, s37, s1
	s_mul_hi_i32 s7, s6, 0x88000
	s_mul_i32 s6, s6, 0x88000
	v_ashrrev_i32_e32 v14, 3, v70
	v_lshl_add_u64 v[0:1], s[64:65], 0, v[50:51]
	v_lshlrev_b32_e32 v2, 1, v2
	v_mov_b32_e32 v3, v163
	v_ashrrev_i32_e32 v13, 31, v12
	s_add_u32 s6, s38, s6
	v_lshl_add_u64 v[66:67], v[0:1], 0, v[2:3]
	v_lshlrev_b64 v[0:1], 8, v[12:13]
	v_ashrrev_i32_e32 v15, 31, v14
	s_addc_u32 s7, s39, s7
	v_lshlrev_b32_e32 v71, 4, v70
	v_lshl_add_u64 v[0:1], s[64:65], 0, v[0:1]
	v_lshlrev_b64 v[52:53], 7, v[14:15]
	v_and_b32_e32 v16, 0x70, v71
	v_lshl_add_u64 v[4:5], v[0:1], 0, v[2:3]
	v_lshl_add_u64 v[8:9], s[6:7], 0, v[52:53]
	v_mov_b32_e32 v17, v163
	global_load_dwordx4 v[0:3], v[66:67], off
	s_nop 0
	global_load_dwordx4 v[4:7], v[4:5], off
	v_lshl_add_u64 v[68:69], v[8:9], 0, v[16:17]
	global_load_dwordx4 v[8:11], v[68:69], off
	v_ashrrev_i32_e32 v13, 1, v70
	v_bfi_b32 v18, s68, v13, v70
	v_ashrrev_i32_e32 v19, 31, v18
	v_lshlrev_b64 v[18:19], 7, v[18:19]
	v_lshrrev_b32_e32 v13, 1, v70
	v_lshl_add_u64 v[18:19], s[0:1], 0, v[18:19]
	v_and_b32_e32 v156, 16, v13
	v_mov_b32_e32 v157, v163
	v_lshl_add_u64 v[18:19], v[18:19], 0, v[156:157]
	global_load_dwordx4 v[108:111], v[18:19], off
	global_load_dwordx4 v[104:107], v[18:19], off offset:32
	global_load_dwordx4 v[100:103], v[18:19], off offset:64
	global_load_dwordx4 v[96:99], v[18:19], off offset:96
	v_and_b32_e32 v13, 0xfffff0, v48
	v_lshlrev_b32_e32 v15, 1, v48
	v_and_or_b32 v13, v15, 8, v13
	v_lshrrev_b32_e32 v13, 1, v13
	v_bfe_u32 v17, v20, 5, 2
	v_lshrrev_b32_e32 v15, 1, v48
	v_or_b32_e32 v13, v13, v17
	v_and_b32_e32 v73, 3, v48
	v_lshlrev_b32_e32 v72, 9, v13
	v_and_or_b32 v13, v15, 4, v73
	v_and_b32_e32 v15, 0xfffff0, v12
	v_lshlrev_b32_e32 v12, 1, v12
	v_and_or_b32 v12, v12, 8, v15
	v_lshrrev_b32_e32 v12, 1, v12
	v_or_b32_e32 v12, v12, v17
	v_lshlrev_b32_e32 v13, 6, v13
	v_and_b32_e32 v74, 48, v71
	v_lshlrev_b32_e32 v75, 9, v12
	v_or3_b32 v18, v72, v13, v74
	v_or3_b32 v17, v75, v13, v74
	v_lshlrev_b32_e32 v12, 7, v14
	v_and_b32_e32 v13, 0x70, v70
	v_bitop3_b32 v76, v16, v12, v13 bitop3:0xde
	v_add_co_u32_e32 v12, vcc, s75, v66
	s_movk_i32 s0, 0x6000
	s_nop 0
	v_addc_co_u32_e32 v13, vcc, 0, v67, vcc
	global_load_dwordx4 v[54:57], v[12:13], off
	v_add_co_u32_e32 v12, vcc, s0, v66
	v_and_b32_e32 v49, 31, v70
	s_nop 0
	v_addc_co_u32_e32 v13, vcc, 0, v67, vcc
	v_add_co_u32_e32 v14, vcc, s8, v68
	v_lshlrev_b32_e32 v80, 7, v49
	s_nop 0
	v_addc_co_u32_e32 v15, vcc, 0, v69, vcc
	global_load_dwordx4 v[58:61], v[12:13], off
	global_load_dwordx4 v[62:65], v[14:15], off
	v_and_b32_e32 v81, 0x70, v20
	v_add_u32_e32 v77, 0, v18
	v_add_u32_e32 v78, 0, v17
	v_bitop3_b32 v175, v156, v80, v81 bitop3:0xde
	s_waitcnt vmcnt(3)
	v_add_u32_e32 v79, 0, v76
	v_or_b32_e32 v83, 32, v156
	v_bitop3_b32 v178, v83, v80, v81 bitop3:0xde
	v_and_b32_e32 v82, 63, v70
	s_mov_b32 s0, 0xa000
	v_and_b32_e32 v180, 0xc0, v71
	v_or_b32_e32 v71, 64, v156
	v_bitop3_b32 v177, v71, v80, v81 bitop3:0xde
	v_or_b32_e32 v84, 0x60, v156
	v_bitop3_b32 v176, v84, v80, v81 bitop3:0xde
	s_mov_b32 s8, 0
	s_mov_b32 s9, s8
	s_mov_b32 s10, s8
	s_mov_b32 s11, s8
	s_mov_b32 s12, s8
	s_mov_b32 s13, s8
	s_mov_b32 s14, s8
	s_mov_b32 s15, s8
	s_mov_b32 s16, s8
	s_mov_b32 s17, s8
	s_waitcnt vmcnt(9)
	ds_write_b128 v77, v[0:3]
	s_waitcnt vmcnt(8)
	ds_write_b128 v78, v[4:7]
	v_add_u32_e32 v4, 0, v175
	v_and_b32_e32 v5, 0x3fffffc0, v70
	s_waitcnt vmcnt(7)
	ds_write_b128 v79, v[8:11] offset:49152
	s_waitcnt lgkmcnt(0)
	s_barrier
; DEV int v_st(int k, int c) { const int kk = (k & ~0xC) | ((k & 4) << 1) | ((k & 8) >> 1); return ((kk >> 3) * 4 + (c >> 5)) * 512 + ((kk & 7) * 32 + (c & 31)) * 2; }
; #define SWAIT() asm volatile("s_waitcnt vmcnt(3)" ::: "memory")
; DEV void partialSM(f32x16& p0, f32x16& p1, float& m_reg, float& mn, float& alpha) {
;   constexpr float C = AT_SCALE * 1.4426950408889634f;
;   float pmax = p0[0];
; #pragma unroll
;   for (int r = 1; r < 16; ++r) pmax = fmaxf(pmax, p0[r]);
; #pragma unroll
;   for (int r = 0; r < 16; ++r) pmax = fmaxf(pmax, p1[r]);
;   { auto rr = __builtin_amdgcn_permlane32_swap(__float_as_uint(pmax), __float_as_uint(pmax), false, false);
;     pmax = fmaxf(__uint_as_float(rr[0]), __uint_as_float(rr[1])); }
;   if (__builtin_expect(__all(pmax - m_reg <= AT_THR / AT_SCALE), 1)) { mn = m_reg; alpha = 1.f; }
;   else { mn = fmaxf(m_reg, pmax); alpha = __builtin_amdgcn_exp2f((m_reg - mn) * C); m_reg = mn; }
;   float mnC = -mn * C;
; #pragma unroll
;   for (int r = 0; r < 16; ++r) p0[r] = fmaf(p0[r], C, mnC);
; #pragma unroll
;   for (int r = 0; r < 16; ++r) p1[r] = fmaf(p1[r], C, mnC);
; #pragma unroll
;   for (int r = 0; r < 16; ++r) p0[r] = __builtin_amdgcn_exp2f(p0[r]);
; }
; DEV void attn_pass(const u16* __restrict__ Qb, const u16* __restrict__ Kh, const u16* __restrict__ Vh, int seq, f32x16* o, float* rli) {
;     ...
;   float m_reg = -1e30f, l_reg = 0; bf16x8 qr[4];
; #pragma unroll
;   for (int d = 0; d < 4; ++d) o[d] = f32x16{};
;   const u16* Qw = Qb + (size_t)(wid * 32 + r32) * 64 + hi * 8;
; #pragma unroll
;   for (int d0 = 0; d0 < 4; ++d0) qr[d0] = *reinterpret_cast<const bf16x8*>(Qw + d0 * 16);
;   const int sr = tid >> 4, sc = (tid & 15) * 8, vst0 = v_st(sr, sc), vst1 = v_st(32 + sr, sc);
;   const int kr = tid >> 3, kc = (tid & 7) * 8, kst = KSWZ64(kr, kc * 2);
;   const int vb0 = (int)(uintptr_t)(__attribute__((address_space(3))) char*)V_lds + v_rd_base(lane);
;   struct { bf16x8 vs0, vs1, ks0; } sr_[2];
;     ...
;   f32x16 pA0, pA1, pB0, pB1; float mnA, mnB, alA, alB; bf16x8 pa0, pa1, pa2, pa3; const int NT = seq / 64;
;   constexpr int SE = 0, SO = 1;
;   SLOAD(SE, 0); SLOAD(SO, 64);
;   asm volatile("s_waitcnt vmcnt(3)" ::: "memory"); SWRITE(0, SE); __syncthreads();
;   if (2 < NT) SLOAD(SE, 2 * 64);
;   qkt(pA0, pA1, K_lds, qr, r32, hi); partialSM(pA0, pA1, m_reg, mnA, alA);
;   SWAIT(); SWRITE(1, SO); __syncthreads();
	ds_read_b128 v[0:3], v4 offset:49152
	v_lshl_add_u32 v157, v5, 2, s48
	ds_read_b128 v[4:7], v4 offset:53248
	v_add_u32_e32 v8, 0, v178
	s_waitcnt vmcnt(6) lgkmcnt(1)
	v_mfma_f32_32x32x16_bf16 v[16:31], v[0:3], v[108:111], 0
	ds_read_b128 v[0:3], v8 offset:49152
	s_mov_b32 s18, s8
	s_mov_b32 s19, s8
	s_mov_b32 s20, s8
	s_mov_b32 s21, s8
	s_mov_b32 s22, s8
	s_mov_b32 s23, s8
	s_waitcnt lgkmcnt(1)
	v_mfma_f32_32x32x16_bf16 v[32:47], v[4:7], v[108:111], 0
	v_lshlrev_b32_e32 v4, 3, v82
	v_lshlrev_b32_e32 v5, 1, v70
	v_and_b32_e32 v179, 24, v4
	v_and_b32_e32 v181, 32, v5
	v_and_b32_e32 v182, 0x100, v4
	ds_read_b128 v[4:7], v8 offset:53248
	v_add_co_u32_e32 v8, vcc, s75, v68
	s_waitcnt vmcnt(5) lgkmcnt(0)
	v_mfma_f32_32x32x16_bf16 v[32:47], v[4:7], v[104:107], v[32:47]
	v_addc_co_u32_e32 v9, vcc, 0, v69, vcc
	v_add_co_u32_e32 v10, vcc, s0, v66
	s_mov_b32 s0, 0x8000
	s_nop 0
	v_addc_co_u32_e32 v11, vcc, 0, v67, vcc
	v_add_co_u32_e32 v4, vcc, s0, v66
	v_add_u32_e32 v6, 0, v177
	s_nop 0
	v_addc_co_u32_e32 v5, vcc, 0, v67, vcc
	v_mfma_f32_32x32x16_bf16 v[16:31], v[0:3], v[104:107], v[16:31]
	ds_read_b128 v[0:3], v6 offset:49152
	global_load_dwordx4 v[120:123], v[8:9], off
	global_load_dwordx4 v[112:115], v[10:11], off
	global_load_dwordx4 v[116:119], v[4:5], off
	v_add_u32_e32 v8, 0, v176
	ds_read_b128 v[4:7], v6 offset:53248
	ds_read_b128 v[66:69], v8 offset:53248
	v_lshl_add_u32 v173, v49, 2, v157
	s_waitcnt vmcnt(7) lgkmcnt(2)
	v_mfma_f32_32x32x16_bf16 v[16:31], v[0:3], v[100:103], v[16:31]
	ds_read_b128 v[0:3], v8 offset:49152
	s_waitcnt vmcnt(3)
	s_waitcnt vmcnt(5)
	ds_write_b128 v77, v[54:57] offset:16384
	s_waitcnt vmcnt(4)
	ds_write_b128 v78, v[58:61] offset:16384
	s_waitcnt vmcnt(3)
	ds_write_b128 v79, v[62:65] offset:57344
	v_mov_b32_e32 v54, 0xf149f2ca
	s_mov_b32 s0, 0x10000
	s_mov_b32 s1, 0xe000
	s_mov_b32 s46, 2
	s_waitcnt lgkmcnt(5)
	v_mfma_f32_32x32x16_bf16 v[32:47], v[4:7], v[100:103], v[32:47]
	s_mov_b32 s47, 1
	s_mov_b32 s48, 4
	s_mov_b32 s64, 3
	v_cmp_gt_u32_e64 s[6:7], 32, v82
	v_add_u32_e32 v183, 0x10000, v76
	v_add_u32_e32 v184, 0, v80
	v_bitop3_b32 v198, v156, s0, v81 bitop3:0xde
	s_waitcnt lgkmcnt(3)
	v_mfma_f32_32x32x16_bf16 v[16:31], v[0:3], v[96:99], v[16:31]
	v_mov_b64_e32 v[0:1], s[8:9]
	v_mov_b64_e32 v[2:3], s[10:11]
	v_mov_b64_e32 v[4:5], s[12:13]
	v_mov_b64_e32 v[6:7], s[14:15]
	v_mov_b64_e32 v[8:9], s[16:17]
	v_mov_b64_e32 v[10:11], s[18:19]
	v_mov_b64_e32 v[12:13], s[20:21]
	v_mfma_f32_32x32x16_bf16 v[32:47], v[66:69], v[96:99], v[32:47]
	s_nop 3
	v_max_f32_e32 v66, v17, v17
	v_max_f32_e32 v67, v16, v16
	v_max_f32_e32 v66, v67, v66
	v_max3_f32 v66, v66, v18, v19
	v_max3_f32 v66, v66, v20, v21
	v_max3_f32 v66, v66, v22, v23
	v_max3_f32 v66, v66, v24, v25
	v_max3_f32 v66, v66, v26, v27
	v_max3_f32 v66, v66, v28, v29
	v_max3_f32 v66, v66, v30, v31
	v_max3_f32 v66, v66, v32, v33
	v_max3_f32 v66, v66, v34, v35
	v_max3_f32 v66, v66, v36, v37
	v_max3_f32 v66, v66, v38, v39
	v_max3_f32 v66, v66, v40, v41
	v_max3_f32 v66, v66, v42, v43
	v_max3_f32 v66, v66, v44, v45
	v_max3_f32 v66, v66, v46, v47
	v_mov_b32_e32 v67, v66
	s_nop 1
	v_permlane32_swap_b32_e32 v66, v67
	v_max_f32_e32 v67, v67, v67
	v_max_f32_e32 v66, v66, v66
	v_max_f32_e32 v66, v66, v67
	v_mov_b64_e32 v[14:15], s[22:23]
	v_add_f32_e32 v67, 0x7149f2ca, v66
	s_mov_b32 s18, 0x42800000
	v_cmp_ge_f32_e32 vcc, s18, v67
	s_cmp_eq_u64 vcc, exec
	v_max_f32_e32 v55, 0xf149f2ca, v66
	s_cselect_b64 vcc, -1, 0
	v_cndmask_b32_e32 v140, v55, v54, vcc
	v_mul_f32_e32 v54, 0xbe38aa3b, v140
	v_fmamk_f32 v16, v16, 0x3e38aa3b, v54
	v_exp_f32_e32 v150, v16
	v_fmamk_f32 v16, v17, 0x3e38aa3b, v54
	v_exp_f32_e32 v170, v16
	v_fmamk_f32 v16, v18, 0x3e38aa3b, v54
	v_exp_f32_e32 v151, v16
	v_fmamk_f32 v16, v19, 0x3e38aa3b, v54
	v_exp_f32_e32 v171, v16
	v_fmamk_f32 v16, v20, 0x3e38aa3b, v54
	v_exp_f32_e32 v168, v16
	v_fmamk_f32 v16, v21, 0x3e38aa3b, v54
	v_exp_f32_e32 v217, v16
	v_fmamk_f32 v16, v22, 0x3e38aa3b, v54
	v_exp_f32_e32 v169, v16
	v_fmamk_f32 v16, v23, 0x3e38aa3b, v54
	v_exp_f32_e32 v218, v16
	v_fmamk_f32 v16, v24, 0x3e38aa3b, v54
	v_exp_f32_e32 v142, v16
	v_fmamk_f32 v16, v25, 0x3e38aa3b, v54
	v_exp_f32_e32 v146, v16
	v_fmamk_f32 v16, v26, 0x3e38aa3b, v54
	v_exp_f32_e32 v143, v16
	v_fmamk_f32 v16, v27, 0x3e38aa3b, v54
	v_exp_f32_e32 v147, v16
	v_fmamk_f32 v16, v28, 0x3e38aa3b, v54
	v_exp_f32_e32 v144, v16
	v_fmamk_f32 v16, v29, 0x3e38aa3b, v54
	v_exp_f32_e32 v148, v16
	v_fmamk_f32 v16, v30, 0x3e38aa3b, v54
	v_exp_f32_e32 v145, v16
	v_add3_u32 v16, v182, 0, v180
	v_add3_u32 v199, v16, v181, v179
	v_lshlrev_b32_e32 v16, 5, v48
	v_pk_fma_f32 v[132:133], v[38:39], s[86:87], v[54:55] op_sel_hi:[1,0,0]
	v_sub_f32_e32 v38, 0xf149f2ca, v55
	v_and_b32_e32 v16, 0x100, v16
	v_lshlrev_b32_e32 v17, 6, v73
	v_and_b32_e32 v18, 7, v70
	v_mul_f32_e32 v38, 0x3e38aa3b, v38
	v_or3_b32 v20, v75, v16, v17
	v_or3_b32 v21, v72, v16, v17
	v_lshl_add_u64 v[16:17], s[62:63], 0, v[52:53]
	v_lshlrev_b32_e32 v18, 4, v18
	v_mov_b32_e32 v19, v163
	v_exp_f32_e32 v38, v38
	v_lshl_add_u64 v[16:17], v[16:17], 0, v[18:19]
	v_and_b32_e32 v18, 15, v70
	v_pk_fma_f32 v[124:125], v[46:47], s[86:87], v[54:55] op_sel_hi:[1,0,0]
	v_pk_fma_f32 v[126:127], v[44:45], s[86:87], v[54:55] op_sel_hi:[1,0,0]
	v_pk_fma_f32 v[128:129], v[42:43], s[86:87], v[54:55] op_sel_hi:[1,0,0]
	v_pk_fma_f32 v[130:131], v[40:41], s[86:87], v[54:55] op_sel_hi:[1,0,0]
	v_pk_fma_f32 v[134:135], v[36:37], s[86:87], v[54:55] op_sel_hi:[1,0,0]
	v_pk_fma_f32 v[136:137], v[34:35], s[86:87], v[54:55] op_sel_hi:[1,0,0]
	v_pk_fma_f32 v[138:139], v[32:33], s[86:87], v[54:55] op_sel_hi:[1,0,0]
	v_fmac_f32_e32 v54, 0x3e38aa3b, v31
; DEV void qkt(f32x16& p0, f32x16& p1, const char* Ks, const bf16x8* qr, int r32, int hi) {
;   p0 = f32x16{}; p1 = f32x16{};
; #pragma unroll
;   for (int d0 = 0; d0 < 4; ++d0) { int cb = (d0 * 16 + hi * 8) * 2;
;     bf16x8 b0 = *reinterpret_cast<const bf16x8*>(Ks + KSWZ64(r32, cb));
;     bf16x8 b1 = *reinterpret_cast<const bf16x8*>(Ks + KSWZ64(32 + r32, cb));
;     p0 = __builtin_amdgcn_mfma_f32_32x32x16_bf16(b0, qr[d0], p0, 0, 0, 0);
;     p1 = __builtin_amdgcn_mfma_f32_32x32x16_bf16(b1, qr[d0], p1, 0, 0, 0); }
; }
; DEV int v_st(int k, int c) { const int kk = (k & ~0xC) | ((k & 4) << 1) | ((k & 8) >> 1); return ((kk >> 3) * 4 + (c >> 5)) * 512 + ((kk & 7) * 32 + (c & 31)) * 2; }
; DEV int v_rd_base(int lane) { return ((lane & 3) << 3) | (((lane >> 2) & 3) << 6) | (((lane >> 4) & 1) << 5) | (((lane >> 5) & 1) << 8); }
; template <int OFF> DEV s16x4 tr_read(int vb) {
;   s16x4 r; asm volatile("ds_read_b64_tr_b16 %0, %1 offset:%2" : "=&v"(r) : "v"(vb), "i"(OFF) : "memory"); return r;
; }
; template <int D0> DEV void pv_one(f32x16& od, int vb, bf16x8 pa0, bf16x8 pa1, bf16x8 pa2, bf16x8 pa3) {
;   const s16x4 l0 = tr_read<v_rd_off(D0, 0, 0)>(vb), h0 = tr_read<v_rd_off(D0, 0, 1)>(vb), l1 = tr_read<v_rd_off(D0, 1, 0)>(vb), h1 = tr_read<v_rd_off(D0, 1, 1)>(vb);
;   const s16x4 l2 = tr_read<v_rd_off(D0, 2, 0)>(vb), h2 = tr_read<v_rd_off(D0, 2, 1)>(vb), l3 = tr_read<v_rd_off(D0, 3, 0)>(vb), h3 = tr_read<v_rd_off(D0, 3, 1)>(vb);
;   asm volatile("s_waitcnt lgkmcnt(0)" ::: "memory"); SBAR();
;     ...
;   od = __builtin_amdgcn_mfma_f32_32x32x16_bf16(pa0, PK(l0, h0), od, 0, 0, 0);
;   od = __builtin_amdgcn_mfma_f32_32x32x16_bf16(pa1, PK(l1, h1), od, 0, 0, 0);
;   od = __builtin_amdgcn_mfma_f32_32x32x16_bf16(pa2, PK(l2, h2), od, 0, 0, 0);
;   od = __builtin_amdgcn_mfma_f32_32x32x16_bf16(pa3, PK(l3, h3), od, 0, 0, 0);
;     ...
; }
; DEV void pv_d0(f32x16* o, int vb, bf16x8 pa0, bf16x8 pa1, bf16x8 pa2, bf16x8 pa3) {
;   pv_one<0>(o[0], vb, pa0, pa1, pa2, pa3); pv_one<1>(o[1], vb, pa0, pa1, pa2, pa3); pv_one<2>(o[2], vb, pa0, pa1, pa2, pa3); pv_one<3>(o[3], vb, pa0, pa1, pa2, pa3);
; DEV void attn_pass(const u16* __restrict__ Qb, const u16* __restrict__ Kh, const u16* __restrict__ Vh, int seq, f32x16* o, float* rli) {
;     ...
;   for (int j = 1; j + 1 < NT; j += 2) {
;     const int bm1 = (j - 1) % 3, b0 = j % 3, b1 = (j + 1) % 3, b2 = (j + 2) % 3;
	v_lshl_add_u64 v[158:159], s[96:97], 0, v[16:17]
	v_lshl_add_u64 v[16:17], s[52:53], 0, v[50:51]
	v_lshlrev_b32_e32 v18, 4, v18
	v_exp_f32_e32 v149, v54
	v_lshl_add_u64 v[16:17], v[16:17], 0, v[18:19]
	v_lshl_add_u64 v[160:161], s[96:97], 0, v[16:17]
	v_add3_u32 v16, v182, s49, v180
	v_cndmask_b32_e64 v185, v38, 1.0, vcc
	v_add_u32_e32 v206, 0x8000, v20
	v_add_u32_e32 v207, 0x8000, v21
	v_add_u32_e32 v209, 0xc000, v20
	v_add_u32_e32 v210, 0xc000, v21
	v_add3_u32 v211, v16, v181, v179
	v_mov_b64_e32 v[62:63], v[14:15]
	v_mov_b64_e32 v[46:47], v[14:15]
	v_mov_b64_e32 v[30:31], v[14:15]
	v_bitop3_b32 v200, v83, s0, v81 bitop3:0xde
	v_bitop3_b32 v201, v156, s1, v81 bitop3:0xde
	v_bitop3_b32 v202, v71, s0, v81 bitop3:0xde
	v_bitop3_b32 v203, v83, s1, v81 bitop3:0xde
	v_bitop3_b32 v204, v84, s0, v81 bitop3:0xde
	v_add_u32_e32 v205, 0, v74
	v_add_u32_e32 v208, 0x12000, v76
	v_bitop3_b32 v212, v71, s1, v81 bitop3:0xde
	v_bitop3_b32 v213, v84, s1, v81 bitop3:0xde
	v_mov_b32_e32 v174, 0
	v_mov_b64_e32 v[60:61], v[12:13]
	v_mov_b64_e32 v[58:59], v[10:11]
	v_mov_b64_e32 v[56:57], v[8:9]
	v_mov_b64_e32 v[54:55], v[6:7]
	v_mov_b64_e32 v[52:53], v[4:5]
	v_mov_b64_e32 v[50:51], v[2:3]
	v_mov_b64_e32 v[48:49], v[0:1]
	v_mov_b64_e32 v[44:45], v[12:13]
	v_mov_b64_e32 v[42:43], v[10:11]
	v_mov_b64_e32 v[40:41], v[8:9]
	v_mov_b64_e32 v[38:39], v[6:7]
	v_mov_b64_e32 v[36:37], v[4:5]
	v_mov_b64_e32 v[34:35], v[2:3]
	v_mov_b64_e32 v[32:33], v[0:1]
	v_mov_b64_e32 v[28:29], v[12:13]
	v_mov_b64_e32 v[26:27], v[10:11]
	v_mov_b64_e32 v[24:25], v[8:9]
	v_mov_b64_e32 v[22:23], v[6:7]
	v_mov_b64_e32 v[20:21], v[4:5]
	v_mov_b64_e32 v[18:19], v[2:3]
	v_mov_b64_e32 v[16:17], v[0:1]
	s_waitcnt lgkmcnt(0)
	s_barrier
.LBB0_90:
	s_mul_hi_u32 s1, s9, 0xaaaaaaab
	s_lshr_b32 s1, s1, 1
	s_mul_i32 s1, s1, 0xc000
	v_subrev_u32_e32 v190, s1, v199
	s_mul_hi_u32 s1, s47, 0xaaaaaaab
	s_mul_hi_u32 s0, s46, 0xaaaaaaab
	s_lshr_b32 s12, s1, 1
	s_lshr_b32 s0, s0, 1
	s_mul_i32 s1, s12, 0x6000
	s_mul_i32 s15, s0, 0x6000
	v_subrev_u32_e32 v64, s1, v201
	s_mul_i32 s0, s0, 0xc000
	v_subrev_u32_e32 v219, s15, v183
	v_subrev_u32_e32 v164, s1, v203
	v_subrev_u32_e32 v220, s0, v206
	v_subrev_u32_e32 v221, s0, v207
	v_subrev_u32_e32 v191, s1, v212
	v_subrev_u32_e32 v192, s1, v213
	v_add_u32_e32 v141, s14, v184
	v_add_u32_e32 v68, v141, v64
	ds_read_b128 v[64:67], v68
	ds_read_b128 v[68:71], v68 offset:4096
	v_add_u32_e32 v186, v141, v164
	ds_read_b128 v[164:167], v186
	ds_read_b128 v[186:189], v186 offset:4096
	v_exp_f32_e32 v134, v134
	s_waitcnt lgkmcnt(3)
	v_mfma_f32_32x32x16_bf16 v[80:95], v[64:67], v[108:111], 0
	v_exp_f32_e32 v135, v135
	v_exp_f32_e32 v132, v132
	v_exp_f32_e32 v133, v133
	v_exp_f32_e32 v130, v130
	v_exp_f32_e32 v131, v131
	v_exp_f32_e32 v128, v128
	v_exp_f32_e32 v129, v129
	s_waitcnt lgkmcnt(2)
	v_mfma_f32_32x32x16_bf16 v[64:79], v[68:71], v[108:111], 0
	v_exp_f32_e32 v126, v126
	v_exp_f32_e32 v127, v127
	v_exp_f32_e32 v124, v124
	v_exp_f32_e32 v125, v125
	s_waitcnt lgkmcnt(1)
	v_mfma_f32_32x32x16_bf16 v[80:95], v[164:167], v[104:107], v[80:95]
	s_waitcnt lgkmcnt(0)
	v_mfma_f32_32x32x16_bf16 v[64:79], v[186:189], v[104:107], v[64:79]
	v_add_u32_e32 v186, v141, v191
	ds_read_b128 v[164:167], v186
	ds_read_b128 v[186:189], v186 offset:4096
	s_waitcnt lgkmcnt(1)
	v_mfma_f32_32x32x16_bf16 v[80:95], v[164:167], v[100:103], v[80:95]
	s_waitcnt lgkmcnt(0)
	v_mfma_f32_32x32x16_bf16 v[64:79], v[186:189], v[100:103], v[64:79]
	v_add_u32_e32 v186, v141, v192
	ds_read_b128 v[164:167], v186
	ds_read_b128 v[186:189], v186 offset:4096
	s_waitcnt lgkmcnt(1)
	v_mfma_f32_32x32x16_bf16 v[80:95], v[164:167], v[96:99], v[80:95]
	v_exp_f32_e32 v166, v136
	v_add_f32_e32 v136, v170, v150
	v_add_f32_e32 v136, v151, v136
	v_add_f32_e32 v136, v171, v136
	v_add_f32_e32 v136, v168, v136
	v_add_f32_e32 v136, v217, v136
	v_add_f32_e32 v136, v169, v136
	v_add_f32_e32 v136, v218, v136
	v_add_f32_e32 v136, v142, v136
	v_add_f32_e32 v136, v146, v136
	v_add_f32_e32 v136, v143, v136
	v_add_f32_e32 v136, v147, v136
	v_exp_f32_e32 v164, v138
	v_add_f32_e32 v136, v144, v136
	v_exp_f32_e32 v165, v139
	v_add_f32_e32 v136, v148, v136
	v_add_f32_e32 v136, v145, v136
	v_exp_f32_e32 v167, v137
	v_add_f32_e32 v136, v149, v136
	v_add_f32_e32 v136, v164, v136
	v_add_f32_e32 v136, v165, v136
	v_add_f32_e32 v136, v166, v136
	v_add_f32_e32 v136, v167, v136
	v_add_f32_e32 v136, v134, v136
	v_add_f32_e32 v136, v135, v136
	v_add_f32_e32 v136, v132, v136
	v_add_f32_e32 v136, v133, v136
	v_add_f32_e32 v136, v130, v136
	v_add_f32_e32 v136, v131, v136
	s_waitcnt lgkmcnt(0)
; #define SBAR() __builtin_amdgcn_sched_barrier(0)
; DEV void finishSM(f32x16& p0, f32x16& p1, float alpha, float& l_reg, bf16x8& pa0, bf16x8& pa1, bf16x8& pa2, bf16x8& pa3) {
;     ...
;   { auto rr = __builtin_amdgcn_permlane32_swap(__float_as_uint(ps), __float_as_uint(ps), false, false);
;     ps = __uint_as_float(rr[0]) + __uint_as_float(rr[1]); }
;   l_reg = l_reg * alpha + ps;
;     ...
;   PK4(p0, 0, pa0); PK4(p0, 8, pa1); PK4(p1, 0, pa2); PK4(p1, 8, pa3);
;     ...
; }
; DEV void qkt(f32x16& p0, f32x16& p1, const char* Ks, const bf16x8* qr, int r32, int hi) {
;   p0 = f32x16{}; p1 = f32x16{};
; #pragma unroll
;   for (int d0 = 0; d0 < 4; ++d0) { int cb = (d0 * 16 + hi * 8) * 2;
;     bf16x8 b0 = *reinterpret_cast<const bf16x8*>(Ks + KSWZ64(r32, cb));
;     bf16x8 b1 = *reinterpret_cast<const bf16x8*>(Ks + KSWZ64(32 + r32, cb));
;     p0 = __builtin_amdgcn_mfma_f32_32x32x16_bf16(b0, qr[d0], p0, 0, 0, 0);
;     p1 = __builtin_amdgcn_mfma_f32_32x32x16_bf16(b1, qr[d0], p1, 0, 0, 0); }
; }
; DEV int v_st(int k, int c) { const int kk = (k & ~0xC) | ((k & 4) << 1) | ((k & 8) >> 1); return ((kk >> 3) * 4 + (c >> 5)) * 512 + ((kk & 7) * 32 + (c & 31)) * 2; }
; DEV int v_rd_base(int lane) { return ((lane & 3) << 3) | (((lane >> 2) & 3) << 6) | (((lane >> 4) & 1) << 5) | (((lane >> 5) & 1) << 8); }
; template <int OFF> DEV s16x4 tr_read(int vb) {
;   s16x4 r; asm volatile("ds_read_b64_tr_b16 %0, %1 offset:%2" : "=&v"(r) : "v"(vb), "i"(OFF) : "memory"); return r;
; }
; template <int D0> DEV void pv_one(f32x16& od, int vb, bf16x8 pa0, bf16x8 pa1, bf16x8 pa2, bf16x8 pa3) {
;   const s16x4 l0 = tr_read<v_rd_off(D0, 0, 0)>(vb), h0 = tr_read<v_rd_off(D0, 0, 1)>(vb), l1 = tr_read<v_rd_off(D0, 1, 0)>(vb), h1 = tr_read<v_rd_off(D0, 1, 1)>(vb);
;   const s16x4 l2 = tr_read<v_rd_off(D0, 2, 0)>(vb), h2 = tr_read<v_rd_off(D0, 2, 1)>(vb), l3 = tr_read<v_rd_off(D0, 3, 0)>(vb), h3 = tr_read<v_rd_off(D0, 3, 1)>(vb);
;   asm volatile("s_waitcnt lgkmcnt(0)" ::: "memory"); SBAR();
;     ...
;   od = __builtin_amdgcn_mfma_f32_32x32x16_bf16(pa0, PK(l0, h0), od, 0, 0, 0);
;   od = __builtin_amdgcn_mfma_f32_32x32x16_bf16(pa1, PK(l1, h1), od, 0, 0, 0);
;   od = __builtin_amdgcn_mfma_f32_32x32x16_bf16(pa2, PK(l2, h2), od, 0, 0, 0);
;   od = __builtin_amdgcn_mfma_f32_32x32x16_bf16(pa3, PK(l3, h3), od, 0, 0, 0);
;     ...
; }
; DEV void pv_d0(f32x16* o, int vb, bf16x8 pa0, bf16x8 pa1, bf16x8 pa2, bf16x8 pa3) {
	v_mfma_f32_32x32x16_bf16 v[64:79], v[186:189], v[96:99], v[64:79]
	v_add_f32_e32 v136, v128, v136
	v_add_f32_e32 v136, v129, v136
	v_add_f32_e32 v136, v126, v136
	v_add_f32_e32 v136, v127, v136
	v_add_f32_e32 v136, v124, v136
	v_add_f32_e32 v214, v125, v136
	v_mov_b32_e32 v215, v214
	v_cvt_pk_bf16_f32 v136, v150, v170
	v_cvt_pk_bf16_f32 v138, v168, v217
	s_nop 1
	v_permlane32_swap_b32_e32 v214, v215
	v_cvt_pk_bf16_f32 v137, v151, v171
	v_cvt_pk_bf16_f32 v139, v169, v218
	v_permlane32_swap_b32_e32 v136, v138
	v_cvt_pk_bf16_f32 v142, v142, v146
	v_cvt_pk_bf16_f32 v143, v143, v147
	v_cvt_pk_bf16_f32 v144, v144, v148
	v_cvt_pk_bf16_f32 v145, v145, v149
	v_cvt_pk_bf16_f32 v146, v164, v165
	v_cvt_pk_bf16_f32 v147, v166, v167
	v_cvt_pk_bf16_f32 v148, v134, v135
	v_cvt_pk_bf16_f32 v149, v132, v133
	v_cvt_pk_bf16_f32 v164, v130, v131
	v_cvt_pk_bf16_f32 v165, v128, v129
	v_cvt_pk_bf16_f32 v166, v126, v127
	v_cvt_pk_bf16_f32 v167, v124, v125
	v_permlane32_swap_b32_e32 v137, v139
	v_permlane32_swap_b32_e32 v142, v144
	v_permlane32_swap_b32_e32 v143, v145
	v_permlane32_swap_b32_e32 v146, v148
	v_permlane32_swap_b32_e32 v147, v149
	v_permlane32_swap_b32_e32 v164, v166
	v_permlane32_swap_b32_e32 v165, v167
	v_lshl_add_u64 v[168:169], v[160:161], 0, s[82:83]
	v_add_co_u32_e32 v124, vcc, s94, v168
	v_lshl_add_u64 v[170:171], v[158:159], 0, s[82:83]
	s_nop 0
	v_addc_co_u32_e32 v125, vcc, 0, v169, vcc
	v_add_co_u32_e32 v128, vcc, s95, v168
	s_mov_b32 s0, 0x1868e000
	s_nop 0
	v_addc_co_u32_e32 v129, vcc, 0, v169, vcc
	v_add_co_u32_e32 v132, vcc, s0, v170
	global_load_dwordx4 v[124:127], v[124:125], off
	s_nop 0
	global_load_dwordx4 v[128:131], v[128:129], off
	v_addc_co_u32_e32 v133, vcc, 0, v171, vcc
	global_load_dwordx4 v[132:135], v[132:133], off
	v_add_u32_e32 v150, s8, v190
	ds_read_b64_tr_b16 v[186:187], v150 offset:0
	ds_read_b64_tr_b16 v[188:189], v150 offset:0x800
	ds_read_b64_tr_b16 v[190:191], v150 offset:0x1000
	ds_read_b64_tr_b16 v[192:193], v150 offset:0x1800
	ds_read_b64_tr_b16 v[222:223], v150 offset:0x2000
	ds_read_b64_tr_b16 v[224:225], v150 offset:0x2800
	ds_read_b64_tr_b16 v[226:227], v150 offset:0x3000
	ds_read_b64_tr_b16 v[228:229], v150 offset:0x3800
	s_waitcnt lgkmcnt(0)
	s_nop 0
	v_mfma_f32_32x32x16_bf16 v[0:15], v[136:139], v[186:189], v[0:15]
	ds_read_b64_tr_b16 v[186:187], v150 offset:0x200
	ds_read_b64_tr_b16 v[188:189], v150 offset:0xa00
	v_mfma_f32_32x32x16_bf16 v[0:15], v[142:145], v[190:193], v[0:15]
	ds_read_b64_tr_b16 v[190:191], v150 offset:0x1200
	ds_read_b64_tr_b16 v[192:193], v150 offset:0x1a00
	v_mfma_f32_32x32x16_bf16 v[0:15], v[146:149], v[222:225], v[0:15]
	ds_read_b64_tr_b16 v[222:223], v150 offset:0x2200
	ds_read_b64_tr_b16 v[224:225], v150 offset:0x2a00
	v_mfma_f32_32x32x16_bf16 v[0:15], v[164:167], v[226:229], v[0:15]
	ds_read_b64_tr_b16 v[226:227], v150 offset:0x3200
	ds_read_b64_tr_b16 v[228:229], v150 offset:0x3a00
	s_waitcnt lgkmcnt(0)
	v_mfma_f32_32x32x16_bf16 v[48:63], v[136:139], v[186:189], v[48:63]
	ds_read_b64_tr_b16 v[186:187], v150 offset:0x400
	ds_read_b64_tr_b16 v[188:189], v150 offset:0xc00
	v_mfma_f32_32x32x16_bf16 v[48:63], v[142:145], v[190:193], v[48:63]
	ds_read_b64_tr_b16 v[190:191], v150 offset:0x1400
	ds_read_b64_tr_b16 v[192:193], v150 offset:0x1c00
	v_mfma_f32_32x32x16_bf16 v[48:63], v[146:149], v[222:225], v[48:63]
	ds_read_b64_tr_b16 v[222:223], v150 offset:0x2400
	ds_read_b64_tr_b16 v[224:225], v150 offset:0x2c00
	v_mfma_f32_32x32x16_bf16 v[48:63], v[164:167], v[226:229], v[48:63]
	ds_read_b64_tr_b16 v[226:227], v150 offset:0x3400
	ds_read_b64_tr_b16 v[228:229], v150 offset:0x3c00
	s_waitcnt lgkmcnt(0)
	v_mfma_f32_32x32x16_bf16 v[32:47], v[136:139], v[186:189], v[32:47]
	ds_read_b64_tr_b16 v[186:187], v150 offset:0x600
	ds_read_b64_tr_b16 v[188:189], v150 offset:0xe00
	v_mfma_f32_32x32x16_bf16 v[32:47], v[142:145], v[190:193], v[32:47]
	ds_read_b64_tr_b16 v[190:191], v150 offset:0x1600
	ds_read_b64_tr_b16 v[192:193], v150 offset:0x1e00
	v_mfma_f32_32x32x16_bf16 v[32:47], v[146:149], v[222:225], v[32:47]
	ds_read_b64_tr_b16 v[222:223], v150 offset:0x2600
	ds_read_b64_tr_b16 v[224:225], v150 offset:0x2e00
	v_mfma_f32_32x32x16_bf16 v[32:47], v[164:167], v[226:229], v[32:47]
	ds_read_b64_tr_b16 v[226:227], v150 offset:0x3600
	ds_read_b64_tr_b16 v[228:229], v150 offset:0x3e00
	s_waitcnt lgkmcnt(0)
	v_mfma_f32_32x32x16_bf16 v[16:31], v[136:139], v[186:189], v[16:31]
	v_max_f32_e32 v136, v80, v81
	v_max3_f32 v136, v136, v82, v83
	v_max3_f32 v136, v136, v84, v85
	v_max3_f32 v136, v136, v86, v87
	v_max3_f32 v136, v136, v88, v89
	v_max3_f32 v136, v136, v90, v91
	v_max3_f32 v136, v136, v92, v93
	v_max3_f32 v136, v136, v94, v95
	v_mfma_f32_32x32x16_bf16 v[16:31], v[142:145], v[190:193], v[16:31]
	v_max3_f32 v136, v136, v64, v65
	v_max3_f32 v136, v136, v66, v67
	v_max3_f32 v136, v136, v68, v69
	v_max3_f32 v136, v136, v70, v71
	v_max3_f32 v136, v136, v72, v73
	v_max3_f32 v136, v136, v74, v75
	v_max3_f32 v136, v136, v76, v77
	v_max3_f32 v136, v136, v78, v79
	v_mfma_f32_32x32x16_bf16 v[16:31], v[146:149], v[222:225], v[16:31]
	v_mov_b32_e32 v137, v136
	s_nop 1
	v_permlane32_swap_b32_e32 v136, v137
	v_max_f32_e32 v136, v136, v137
	v_sub_f32_e32 v137, v136, v140
	v_cmp_ge_f32_e32 vcc, s18, v137
	v_mfma_f32_32x32x16_bf16 v[16:31], v[164:167], v[226:229], v[16:31]
	s_cmp_eq_u64 vcc, exec
	s_cselect_b64 s[0:1], -1, 0
	s_cbranch_scc1 .Lattn_fast3
	v_max_f32_e32 v136, v140, v136
	v_sub_f32_e32 v137, v140, v136
	v_mul_f32_e32 v137, 0x3e38aa3b, v137
	v_exp_f32_e32 v137, v137
; #define SBAR() __builtin_amdgcn_sched_barrier(0)
; #define SWAIT() asm volatile("s_waitcnt vmcnt(3)" ::: "memory")
; DEV void partialSM(f32x16& p0, f32x16& p1, float& m_reg, float& mn, float& alpha) {
;   constexpr float C = AT_SCALE * 1.4426950408889634f;
;   float pmax = p0[0];
; #pragma unroll
;   for (int r = 1; r < 16; ++r) pmax = fmaxf(pmax, p0[r]);
; #pragma unroll
;   for (int r = 0; r < 16; ++r) pmax = fmaxf(pmax, p1[r]);
;   { auto rr = __builtin_amdgcn_permlane32_swap(__float_as_uint(pmax), __float_as_uint(pmax), false, false);
;     pmax = fmaxf(__uint_as_float(rr[0]), __uint_as_float(rr[1])); }
;   if (__builtin_expect(__all(pmax - m_reg <= AT_THR / AT_SCALE), 1)) { mn = m_reg; alpha = 1.f; }
;   else { mn = fmaxf(m_reg, pmax); alpha = __builtin_amdgcn_exp2f((m_reg - mn) * C); m_reg = mn; }
;   float mnC = -mn * C;
; #pragma unroll
;   for (int r = 0; r < 16; ++r) p0[r] = fmaf(p0[r], C, mnC);
; #pragma unroll
;   for (int r = 0; r < 16; ++r) p1[r] = fmaf(p1[r], C, mnC);
; #pragma unroll
;   for (int r = 0; r < 16; ++r) p0[r] = __builtin_amdgcn_exp2f(p0[r]);
; }
; DEV void attn_pass(const u16* __restrict__ Qb, const u16* __restrict__ Kh, const u16* __restrict__ Vh, int seq, f32x16* o, float* rli) {
;     ...
;   f32x16 pA0, pA1, pB0, pB1; float mnA, mnB, alA, alB; bf16x8 pa0, pa1, pa2, pa3; const int NT = seq / 64;
;   constexpr int SE = 0, SO = 1;
;   SLOAD(SE, 0); SLOAD(SO, 64);
;   asm volatile("s_waitcnt vmcnt(3)" ::: "memory"); SWRITE(0, SE); __syncthreads();
;   if (2 < NT) SLOAD(SE, 2 * 64);
;   qkt(pA0, pA1, K_lds, qr, r32, hi); partialSM(pA0, pA1, m_reg, mnA, alA);
;   SWAIT(); SWRITE(1, SO); __syncthreads();
; #pragma unroll 1
;   for (int j = 1; j + 1 < NT; j += 2) {
;     const int bm1 = (j - 1) % 3, b0 = j % 3, b1 = (j + 1) % 3, b2 = (j + 2) % 3;
;     SBAR(); qkt(pB0, pB1, K_lds + b0 * AT_SHM_K, qr, r32, hi);
;     finishSM(pA0, pA1, alA, l_reg, pa0, pa1, pa2, pa3); SBAR();
;     SLOAD(SO, (j + 2) * 64); SBAR();
;     pv_d0(o, vb0 + bm1 * AT_SHM_V, pa0, pa1, pa2, pa3); partialSM(pB0, pB1, m_reg, mnB, alB);
;     SWAIT(); SWRITE(b1, SE);
;     RESC(alB); __syncthreads();
;     SBAR(); qkt(pA0, pA1, K_lds + b1 * AT_SHM_K, qr, r32, hi);
;     finishSM(pB0, pB1, alB, l_reg, pa0, pa1, pa2, pa3); SBAR();
.Lattn_fast3:
	v_add_u32_e32 v217, s8, v205
	v_cndmask_b32_e64 v216, v137, 1.0, s[0:1]
	s_waitcnt vmcnt(3)
	v_add_u32_e32 v137, v217, v221
	ds_write_b128 v137, v[116:119]
	v_add_u32_e32 v137, v217, v220
	s_add_i32 s13, s14, 0
	ds_write_b128 v137, v[112:115]
	v_add_u32_e32 v137, s13, v219
	v_cmp_gt_f32_e32 vcc, 1.0, v216
	ds_write_b128 v137, v[120:123]
	s_cbranch_vccz .LBB0_94
	s_and_saveexec_b64 s[10:11], s[6:7]
	ds_write_b32 v173, v216 offset:128
	s_or_b64 exec, exec, s[10:11]
	s_waitcnt lgkmcnt(0)
	v_add_u32_e32 v137, v157, v156
	ds_read_b128 v[142:145], v137 offset:224
	ds_read_b128 v[146:149], v137 offset:192
	ds_read_b128 v[164:167], v137 offset:160
	ds_read_b128 v[186:189], v137 offset:128
	s_waitcnt lgkmcnt(3)
	v_pk_mul_f32 v[12:13], v[12:13], v[142:143]
	s_waitcnt lgkmcnt(2)
	v_pk_mul_f32 v[8:9], v[8:9], v[146:147]
	s_waitcnt lgkmcnt(1)
	v_pk_mul_f32 v[4:5], v[4:5], v[164:165]
	v_pk_mul_f32 v[14:15], v[14:15], v[144:145]
	v_pk_mul_f32 v[10:11], v[10:11], v[148:149]
	v_pk_mul_f32 v[6:7], v[6:7], v[166:167]
	s_waitcnt lgkmcnt(0)
	v_pk_mul_f32 v[2:3], v[2:3], v[188:189]
	v_pk_mul_f32 v[0:1], v[0:1], v[186:187]
	v_pk_mul_f32 v[60:61], v[60:61], v[142:143]
	v_pk_mul_f32 v[56:57], v[56:57], v[146:147]
	v_pk_mul_f32 v[52:53], v[52:53], v[164:165]
	v_pk_mul_f32 v[62:63], v[62:63], v[144:145]
	v_pk_mul_f32 v[58:59], v[58:59], v[148:149]
	v_pk_mul_f32 v[54:55], v[54:55], v[166:167]
	v_pk_mul_f32 v[50:51], v[50:51], v[188:189]
	v_pk_mul_f32 v[48:49], v[48:49], v[186:187]
	v_pk_mul_f32 v[44:45], v[44:45], v[142:143]
	v_pk_mul_f32 v[40:41], v[40:41], v[146:147]
	v_pk_mul_f32 v[36:37], v[36:37], v[164:165]
	v_pk_mul_f32 v[46:47], v[46:47], v[144:145]
	v_pk_mul_f32 v[42:43], v[42:43], v[148:149]
	v_pk_mul_f32 v[38:39], v[38:39], v[166:167]
	v_pk_mul_f32 v[34:35], v[34:35], v[188:189]
	v_pk_mul_f32 v[32:33], v[32:33], v[186:187]
	v_pk_mul_f32 v[28:29], v[28:29], v[142:143]
	v_pk_mul_f32 v[24:25], v[24:25], v[146:147]
	v_pk_mul_f32 v[20:21], v[20:21], v[164:165]
	v_pk_mul_f32 v[30:31], v[30:31], v[144:145]
	v_pk_mul_f32 v[26:27], v[26:27], v[148:149]
	v_pk_mul_f32 v[22:23], v[22:23], v[166:167]
	v_pk_mul_f32 v[18:19], v[18:19], v[188:189]
	v_pk_mul_f32 v[16:17], v[16:17], v[186:187]
.LBB0_94:
	v_cndmask_b32_e64 v218, v136, v140, s[0:1]
	v_mul_f32_e32 v148, 0xbe38aa3b, v218
	v_subrev_u32_e32 v137, s15, v198
	v_subrev_u32_e32 v138, s15, v200
	v_subrev_u32_e32 v146, s15, v202
	v_subrev_u32_e32 v147, s15, v204
	v_fmamk_f32 v80, v80, 0x3e38aa3b, v148
	v_fmamk_f32 v81, v81, 0x3e38aa3b, v148
	v_fmamk_f32 v82, v82, 0x3e38aa3b, v148
	v_fmamk_f32 v83, v83, 0x3e38aa3b, v148
	v_fmamk_f32 v84, v84, 0x3e38aa3b, v148
	v_fmamk_f32 v85, v85, 0x3e38aa3b, v148
	v_fmamk_f32 v86, v86, 0x3e38aa3b, v148
	v_fmamk_f32 v87, v87, 0x3e38aa3b, v148
	v_fmamk_f32 v88, v88, 0x3e38aa3b, v148
	v_fmamk_f32 v89, v89, 0x3e38aa3b, v148
	v_fmamk_f32 v90, v90, 0x3e38aa3b, v148
	v_fmamk_f32 v91, v91, 0x3e38aa3b, v148
	v_fmamk_f32 v92, v92, 0x3e38aa3b, v148
	v_fmamk_f32 v93, v93, 0x3e38aa3b, v148
	v_fmamk_f32 v94, v94, 0x3e38aa3b, v148
	v_fmamk_f32 v95, v95, 0x3e38aa3b, v148
	v_fmamk_f32 v149, v64, 0x3e38aa3b, v148
	v_fmamk_f32 v150, v65, 0x3e38aa3b, v148
	v_fmamk_f32 v151, v66, 0x3e38aa3b, v148
	v_fmamk_f32 v164, v67, 0x3e38aa3b, v148
	v_fmamk_f32 v165, v68, 0x3e38aa3b, v148
	v_fmamk_f32 v166, v69, 0x3e38aa3b, v148
	v_fmamk_f32 v167, v70, 0x3e38aa3b, v148
	v_fmamk_f32 v186, v71, 0x3e38aa3b, v148
	v_fmamk_f32 v187, v72, 0x3e38aa3b, v148
	v_fmamk_f32 v188, v73, 0x3e38aa3b, v148
	v_fmamk_f32 v189, v74, 0x3e38aa3b, v148
	v_fmamk_f32 v190, v75, 0x3e38aa3b, v148
	v_fmamk_f32 v191, v76, 0x3e38aa3b, v148
	v_fmamk_f32 v192, v77, 0x3e38aa3b, v148
	v_fmamk_f32 v193, v78, 0x3e38aa3b, v148
	v_fmac_f32_e32 v148, 0x3e38aa3b, v79
	v_exp_f32_e32 v194, v80
	v_exp_f32_e32 v195, v81
	v_exp_f32_e32 v221, v82
	v_exp_f32_e32 v222, v83
	v_exp_f32_e32 v223, v84
	v_exp_f32_e32 v224, v85
	v_exp_f32_e32 v225, v86
	v_exp_f32_e32 v226, v87
	v_exp_f32_e32 v227, v88
	v_exp_f32_e32 v228, v89
	v_exp_f32_e32 v229, v90
	v_exp_f32_e32 v230, v91
	v_exp_f32_e32 v231, v92
	v_exp_f32_e32 v232, v93
	v_exp_f32_e32 v233, v94
	v_exp_f32_e32 v234, v95
	s_waitcnt lgkmcnt(0)
	s_barrier
	v_add_u32_e32 v68, v141, v137
	ds_read_b128 v[64:67], v68
	ds_read_b128 v[68:71], v68 offset:4096
	v_add_u32_e32 v140, v141, v138
	ds_read_b128 v[136:139], v140
	ds_read_b128 v[142:145], v140 offset:4096
	v_add_u32_e32 v140, v141, v146
	s_waitcnt lgkmcnt(3)
	v_mfma_f32_32x32x16_bf16 v[80:95], v[64:67], v[108:111], 0
	v_exp_f32_e32 v146, v151
	v_exp_f32_e32 v151, v167
	v_exp_f32_e32 v167, v189
	v_exp_f32_e32 v189, v193
	s_waitcnt lgkmcnt(2)
	v_mfma_f32_32x32x16_bf16 v[64:79], v[68:71], v[108:111], 0
	s_waitcnt lgkmcnt(1)
	v_mfma_f32_32x32x16_bf16 v[80:95], v[136:139], v[104:107], v[80:95]
	s_waitcnt lgkmcnt(0)
	v_mfma_f32_32x32x16_bf16 v[64:79], v[142:145], v[104:107], v[64:79]
	ds_read_b128 v[136:139], v140
	ds_read_b128 v[142:145], v140 offset:4096
	v_add_u32_e32 v140, v141, v147
	v_exp_f32_e32 v147, v164
	v_exp_f32_e32 v164, v186
	v_exp_f32_e32 v186, v190
	v_exp_f32_e32 v190, v148
	s_waitcnt lgkmcnt(1)
	v_mfma_f32_32x32x16_bf16 v[80:95], v[136:139], v[100:103], v[80:95]
	s_waitcnt lgkmcnt(0)
	v_mfma_f32_32x32x16_bf16 v[64:79], v[142:145], v[100:103], v[64:79]
	ds_read_b128 v[136:139], v140
	ds_read_b128 v[140:143], v140 offset:4096
	v_exp_f32_e32 v144, v149
	v_exp_f32_e32 v145, v150
	v_exp_f32_e32 v149, v165
	v_exp_f32_e32 v150, v166
	v_exp_f32_e32 v165, v187
	v_exp_f32_e32 v166, v188
	s_waitcnt lgkmcnt(1)
; DEV void finishSM(f32x16& p0, f32x16& p1, float alpha, float& l_reg, bf16x8& pa0, bf16x8& pa1, bf16x8& pa2, bf16x8& pa3) {
; #pragma unroll
;   for (int r = 0; r < 16; ++r) p1[r] = __builtin_amdgcn_exp2f(p1[r]);
;   float ps = 0;
; #pragma unroll
;   for (int r = 0; r < 16; ++r) ps += p0[r];
; #pragma unroll
;   for (int r = 0; r < 16; ++r) ps += p1[r];
;   { auto rr = __builtin_amdgcn_permlane32_swap(__float_as_uint(ps), __float_as_uint(ps), false, false);
;     ps = __uint_as_float(rr[0]) + __uint_as_float(rr[1]); }
;   l_reg = l_reg * alpha + ps;
;     ...
;   PK4(p0, 0, pa0); PK4(p0, 8, pa1); PK4(p1, 0, pa2); PK4(p1, 8, pa3);
;     ...
; }
; DEV void qkt(f32x16& p0, f32x16& p1, const char* Ks, const bf16x8* qr, int r32, int hi) {
;   p0 = f32x16{}; p1 = f32x16{};
; #pragma unroll
;   for (int d0 = 0; d0 < 4; ++d0) { int cb = (d0 * 16 + hi * 8) * 2;
;     bf16x8 b0 = *reinterpret_cast<const bf16x8*>(Ks + KSWZ64(r32, cb));
;     bf16x8 b1 = *reinterpret_cast<const bf16x8*>(Ks + KSWZ64(32 + r32, cb));
;     p0 = __builtin_amdgcn_mfma_f32_32x32x16_bf16(b0, qr[d0], p0, 0, 0, 0);
;     p1 = __builtin_amdgcn_mfma_f32_32x32x16_bf16(b1, qr[d0], p1, 0, 0, 0); }
; }
; DEV int v_st(int k, int c) { const int kk = (k & ~0xC) | ((k & 4) << 1) | ((k & 8) >> 1); return ((kk >> 3) * 4 + (c >> 5)) * 512 + ((kk & 7) * 32 + (c & 31)) * 2; }
; DEV int v_rd_base(int lane) { return ((lane & 3) << 3) | (((lane >> 2) & 3) << 6) | (((lane >> 4) & 1) << 5) | (((lane >> 5) & 1) << 8); }
; template <int OFF> DEV s16x4 tr_read(int vb) {
;   s16x4 r; asm volatile("ds_read_b64_tr_b16 %0, %1 offset:%2" : "=&v"(r) : "v"(vb), "i"(OFF) : "memory"); return r;
; }
; template <int D0> DEV void pv_one(f32x16& od, int vb, bf16x8 pa0, bf16x8 pa1, bf16x8 pa2, bf16x8 pa3) {
;   const s16x4 l0 = tr_read<v_rd_off(D0, 0, 0)>(vb), h0 = tr_read<v_rd_off(D0, 0, 1)>(vb), l1 = tr_read<v_rd_off(D0, 1, 0)>(vb), h1 = tr_read<v_rd_off(D0, 1, 1)>(vb);
;   const s16x4 l2 = tr_read<v_rd_off(D0, 2, 0)>(vb), h2 = tr_read<v_rd_off(D0, 2, 1)>(vb), l3 = tr_read<v_rd_off(D0, 3, 0)>(vb), h3 = tr_read<v_rd_off(D0, 3, 1)>(vb);
;   asm volatile("s_waitcnt lgkmcnt(0)" ::: "memory"); SBAR();
;     ...
;   od = __builtin_amdgcn_mfma_f32_32x32x16_bf16(pa0, PK(l0, h0), od, 0, 0, 0);
;   od = __builtin_amdgcn_mfma_f32_32x32x16_bf16(pa1, PK(l1, h1), od, 0, 0, 0);
;   od = __builtin_amdgcn_mfma_f32_32x32x16_bf16(pa2, PK(l2, h2), od, 0, 0, 0);
	v_mfma_f32_32x32x16_bf16 v[80:95], v[136:139], v[96:99], v[80:95]
	v_add_f32_e32 v136, v195, v194
	v_add_f32_e32 v136, v221, v136
	v_add_f32_e32 v136, v222, v136
	v_add_f32_e32 v136, v223, v136
	v_add_f32_e32 v136, v224, v136
	v_add_f32_e32 v136, v225, v136
	v_add_f32_e32 v136, v226, v136
	v_add_f32_e32 v136, v227, v136
	v_add_f32_e32 v136, v228, v136
	v_add_f32_e32 v136, v229, v136
	v_add_f32_e32 v136, v230, v136
	v_add_f32_e32 v136, v231, v136
	v_add_f32_e32 v136, v232, v136
	v_add_f32_e32 v136, v233, v136
	v_add_f32_e32 v136, v234, v136
	v_add_f32_e32 v136, v144, v136
	v_add_f32_e32 v136, v145, v136
	v_add_f32_e32 v136, v146, v136
	v_add_f32_e32 v136, v147, v136
	v_add_f32_e32 v136, v149, v136
	v_add_f32_e32 v136, v150, v136
	v_add_f32_e32 v136, v151, v136
	v_add_f32_e32 v136, v164, v136
	v_exp_f32_e32 v187, v191
	v_add_f32_e32 v136, v165, v136
	v_exp_f32_e32 v188, v192
	v_add_f32_e32 v136, v166, v136
	s_waitcnt lgkmcnt(0)
	v_mfma_f32_32x32x16_bf16 v[64:79], v[140:143], v[96:99], v[64:79]
	v_add_f32_e32 v136, v167, v136
	v_add_f32_e32 v136, v186, v136
	v_add_f32_e32 v136, v187, v136
	v_add_f32_e32 v136, v188, v136
	v_add_f32_e32 v136, v189, v136
	v_add_f32_e32 v219, v190, v136
	v_mov_b32_e32 v220, v219
	v_cvt_pk_bf16_f32 v136, v194, v195
	v_cvt_pk_bf16_f32 v137, v221, v222
	v_cvt_pk_bf16_f32 v138, v223, v224
	v_cvt_pk_bf16_f32 v139, v225, v226
	v_cvt_pk_bf16_f32 v140, v227, v228
	v_cvt_pk_bf16_f32 v141, v229, v230
	v_cvt_pk_bf16_f32 v142, v231, v232
	v_cvt_pk_bf16_f32 v143, v233, v234
	v_cvt_pk_bf16_f32 v144, v144, v145
	v_cvt_pk_bf16_f32 v145, v146, v147
	v_cvt_pk_bf16_f32 v146, v149, v150
	v_cvt_pk_bf16_f32 v147, v151, v164
	v_cvt_pk_bf16_f32 v148, v165, v166
	v_cvt_pk_bf16_f32 v149, v167, v186
	v_cvt_pk_bf16_f32 v150, v187, v188
	v_cvt_pk_bf16_f32 v151, v189, v190
	s_nop 1
	v_permlane32_swap_b32_e32 v219, v220
	v_permlane32_swap_b32_e32 v136, v138
	v_permlane32_swap_b32_e32 v137, v139
	v_permlane32_swap_b32_e32 v140, v142
	v_permlane32_swap_b32_e32 v141, v143
	v_permlane32_swap_b32_e32 v144, v146
	v_permlane32_swap_b32_e32 v145, v147
	v_permlane32_swap_b32_e32 v148, v150
	v_permlane32_swap_b32_e32 v149, v151
	s_cmp_ge_u32 s48, s44
	s_cselect_b64 s[10:11], -1, 0
	s_and_b64 vcc, exec, s[10:11]
	s_cbranch_vccnz .LBB0_96
	v_add_co_u32_e32 v112, vcc, 0x1a810000, v168
	s_nop 1
	v_addc_co_u32_e32 v113, vcc, 0, v169, vcc
	v_add_co_u32_e32 v114, vcc, 0x1a812000, v168
	s_nop 1
	v_addc_co_u32_e32 v115, vcc, 0, v169, vcc
	v_add_co_u32_e32 v120, vcc, 0x18690000, v170
	global_load_dwordx4 v[116:119], v[112:113], off
	s_nop 0
	global_load_dwordx4 v[112:115], v[114:115], off
	v_addc_co_u32_e32 v121, vcc, 0, v171, vcc
	global_load_dwordx4 v[120:123], v[120:121], off
.LBB0_96:
	s_mul_hi_u32 s0, s64, 0xaaaaaaab
	s_lshr_b32 s0, s0, 1
	s_mul_i32 s1, s0, 0x6000
	s_mul_i32 s0, s0, 0xc000
	s_mul_i32 s12, s12, 0xc000
	v_subrev_u32_e32 v194, s1, v208
	v_subrev_u32_e32 v195, s0, v209
	v_subrev_u32_e32 v221, s0, v210
	v_subrev_u32_e32 v164, s12, v211
	v_add_u32_e32 v222, s8, v164
	ds_read_b64_tr_b16 v[164:165], v222 offset:0
	ds_read_b64_tr_b16 v[166:167], v222 offset:0x800
	ds_read_b64_tr_b16 v[168:169], v222 offset:0x1000
	ds_read_b64_tr_b16 v[170:171], v222 offset:0x1800
	ds_read_b64_tr_b16 v[186:187], v222 offset:0x2000
	ds_read_b64_tr_b16 v[188:189], v222 offset:0x2800
	ds_read_b64_tr_b16 v[190:191], v222 offset:0x3000
	ds_read_b64_tr_b16 v[192:193], v222 offset:0x3800
	s_waitcnt lgkmcnt(0)
	s_nop 0
	v_mfma_f32_32x32x16_bf16 v[0:15], v[136:139], v[164:167], v[0:15]
	ds_read_b64_tr_b16 v[164:165], v222 offset:0x200
	ds_read_b64_tr_b16 v[166:167], v222 offset:0xa00
	v_mfma_f32_32x32x16_bf16 v[0:15], v[140:143], v[168:171], v[0:15]
	ds_read_b64_tr_b16 v[168:169], v222 offset:0x1200
	ds_read_b64_tr_b16 v[170:171], v222 offset:0x1a00
	v_mfma_f32_32x32x16_bf16 v[0:15], v[144:147], v[186:189], v[0:15]
	ds_read_b64_tr_b16 v[186:187], v222 offset:0x2200
	ds_read_b64_tr_b16 v[188:189], v222 offset:0x2a00
	v_mfma_f32_32x32x16_bf16 v[0:15], v[148:151], v[190:193], v[0:15]
	ds_read_b64_tr_b16 v[190:191], v222 offset:0x3200
	ds_read_b64_tr_b16 v[192:193], v222 offset:0x3a00
	s_waitcnt lgkmcnt(0)
	v_mfma_f32_32x32x16_bf16 v[48:63], v[136:139], v[164:167], v[48:63]
	ds_read_b64_tr_b16 v[164:165], v222 offset:0x400
	ds_read_b64_tr_b16 v[166:167], v222 offset:0xc00
	v_mfma_f32_32x32x16_bf16 v[48:63], v[140:143], v[168:171], v[48:63]
	ds_read_b64_tr_b16 v[168:169], v222 offset:0x1400
	ds_read_b64_tr_b16 v[170:171], v222 offset:0x1c00
	v_mfma_f32_32x32x16_bf16 v[48:63], v[144:147], v[186:189], v[48:63]
	ds_read_b64_tr_b16 v[186:187], v222 offset:0x2400
	ds_read_b64_tr_b16 v[188:189], v222 offset:0x2c00
	v_mfma_f32_32x32x16_bf16 v[48:63], v[148:151], v[190:193], v[48:63]
	ds_read_b64_tr_b16 v[190:191], v222 offset:0x3400
	ds_read_b64_tr_b16 v[192:193], v222 offset:0x3c00
	s_waitcnt lgkmcnt(0)
	v_mfma_f32_32x32x16_bf16 v[32:47], v[136:139], v[164:167], v[32:47]
	ds_read_b64_tr_b16 v[164:165], v222 offset:0x600
	ds_read_b64_tr_b16 v[166:167], v222 offset:0xe00
	v_mfma_f32_32x32x16_bf16 v[32:47], v[140:143], v[168:171], v[32:47]
	ds_read_b64_tr_b16 v[168:169], v222 offset:0x1600
	ds_read_b64_tr_b16 v[170:171], v222 offset:0x1e00
	v_mfma_f32_32x32x16_bf16 v[32:47], v[144:147], v[186:189], v[32:47]
	ds_read_b64_tr_b16 v[186:187], v222 offset:0x2600
	ds_read_b64_tr_b16 v[188:189], v222 offset:0x2e00
	v_mfma_f32_32x32x16_bf16 v[32:47], v[148:151], v[190:193], v[32:47]
	ds_read_b64_tr_b16 v[190:191], v222 offset:0x3600
	ds_read_b64_tr_b16 v[192:193], v222 offset:0x3e00
	s_waitcnt lgkmcnt(0)
	v_mfma_f32_32x32x16_bf16 v[16:31], v[136:139], v[164:167], v[16:31]
	v_max_f32_e32 v136, v80, v81
	v_max3_f32 v136, v136, v82, v83
	v_max3_f32 v136, v136, v84, v85
	v_max3_f32 v136, v136, v86, v87
	v_max3_f32 v136, v136, v88, v89
	v_max3_f32 v136, v136, v90, v91
	v_max3_f32 v136, v136, v92, v93
	v_max3_f32 v136, v136, v94, v95
	v_mfma_f32_32x32x16_bf16 v[16:31], v[140:143], v[168:171], v[16:31]
	v_max3_f32 v136, v136, v64, v65
	v_max3_f32 v136, v136, v66, v67
	v_max3_f32 v136, v136, v68, v69
	v_max3_f32 v136, v136, v70, v71
	v_max3_f32 v136, v136, v72, v73
	v_max3_f32 v136, v136, v74, v75
	v_max3_f32 v136, v136, v76, v77
	v_max3_f32 v136, v136, v78, v79
	v_mfma_f32_32x32x16_bf16 v[16:31], v[144:147], v[186:189], v[16:31]
	v_mov_b32_e32 v137, v136
	s_nop 1
	v_permlane32_swap_b32_e32 v136, v137
	v_max_f32_e32 v136, v136, v137
	v_sub_f32_e32 v137, v136, v218
	v_cmp_ge_f32_e32 vcc, s18, v137
	v_mfma_f32_32x32x16_bf16 v[16:31], v[148:151], v[190:193], v[16:31]
	s_cmp_eq_u64 vcc, exec
	s_cselect_b64 s[0:1], -1, 0
	s_cbranch_scc1 .Lattn_fast4
	v_max_f32_e32 v136, v218, v136
	v_sub_f32_e32 v137, v218, v136
	v_mul_f32_e32 v137, 0x3e38aa3b, v137
	v_exp_f32_e32 v137, v137

; DEV void finishSM(f32x16& p0, f32x16& p1, float alpha, float& l_reg, bf16x8& pa0, bf16x8& pa1, bf16x8& pa2, bf16x8& pa3) {
; #pragma unroll
;   for (int r = 0; r < 16; ++r) p1[r] = __builtin_amdgcn_exp2f(p1[r]);
;   float ps = 0;
; #pragma unroll
;   for (int r = 0; r < 16; ++r) ps += p0[r];
; #pragma unroll
;   for (int r = 0; r < 16; ++r) ps += p1[r];
;   { auto rr = __builtin_amdgcn_permlane32_swap(__float_as_uint(ps), __float_as_uint(ps), false, false);
;     ps = __uint_as_float(rr[0]) + __uint_as_float(rr[1]); }
;   l_reg = l_reg * alpha + ps;
;     ...
;   PK4(p0, 0, pa0); PK4(p0, 8, pa1); PK4(p1, 0, pa2); PK4(p1, 8, pa3);
;     ...
; }
; DEV void qkt(f32x16& p0, f32x16& p1, const char* Ks, const bf16x8* qr, int r32, int hi) {
;   p0 = f32x16{}; p1 = f32x16{};
; #pragma unroll
;   for (int d0 = 0; d0 < 4; ++d0) { int cb = (d0 * 16 + hi * 8) * 2;
;     bf16x8 b0 = *reinterpret_cast<const bf16x8*>(Ks + KSWZ64(r32, cb));
;     bf16x8 b1 = *reinterpret_cast<const bf16x8*>(Ks + KSWZ64(32 + r32, cb));
;     p0 = __builtin_amdgcn_mfma_f32_32x32x16_bf16(b0, qr[d0], p0, 0, 0, 0);
;     p1 = __builtin_amdgcn_mfma_f32_32x32x16_bf16(b1, qr[d0], p1, 0, 0, 0); }
; }
; DEV int v_st(int k, int c) { const int kk = (k & ~0xC) | ((k & 4) << 1) | ((k & 8) >> 1); return ((kk >> 3) * 4 + (c >> 5)) * 512 + ((kk & 7) * 32 + (c & 31)) * 2; }
; DEV int v_rd_base(int lane) { return ((lane & 3) << 3) | (((lane >> 2) & 3) << 6) | (((lane >> 4) & 1) << 5) | (((lane >> 5) & 1) << 8); }
; template <int OFF> DEV s16x4 tr_read(int vb) {
;   s16x4 r; asm volatile("ds_read_b64_tr_b16 %0, %1 offset:%2" : "=&v"(r) : "v"(vb), "i"(OFF) : "memory"); return r;
; }
; template <int D0> DEV void pv_one(f32x16& od, int vb, bf16x8 pa0, bf16x8 pa1, bf16x8 pa2, bf16x8 pa3) {
;   const s16x4 l0 = tr_read<v_rd_off(D0, 0, 0)>(vb), h0 = tr_read<v_rd_off(D0, 0, 1)>(vb), l1 = tr_read<v_rd_off(D0, 1, 0)>(vb), h1 = tr_read<v_rd_off(D0, 1, 1)>(vb);
;   const s16x4 l2 = tr_read<v_rd_off(D0, 2, 0)>(vb), h2 = tr_read<v_rd_off(D0, 2, 1)>(vb), l3 = tr_read<v_rd_off(D0, 3, 0)>(vb), h3 = tr_read<v_rd_off(D0, 3, 1)>(vb);
;   asm volatile("s_waitcnt lgkmcnt(0)" ::: "memory"); SBAR();
;     ...
;   od = __builtin_amdgcn_mfma_f32_32x32x16_bf16(pa0, PK(l0, h0), od, 0, 0, 0);
;   od = __builtin_amdgcn_mfma_f32_32x32x16_bf16(pa1, PK(l1, h1), od, 0, 0, 0);
;   od = __builtin_amdgcn_mfma_f32_32x32x16_bf16(pa2, PK(l2, h2), od, 0, 0, 0);
.LBB0_102:
	v_or_b32_e32 v64, v179, v180
	v_or3_b32 v64, v64, v181, v182
	v_add_u32_e32 v112, 0, v64
	v_add_u32_e32 v68, s45, v175
	ds_read_b128 v[64:67], v68 offset:49152
	ds_read_b128 v[68:71], v68 offset:53248
	v_add_u32_e32 v113, s45, v178
	v_exp_f32_e32 v118, v129
	v_exp_f32_e32 v119, v126
	s_waitcnt lgkmcnt(1)
	v_mfma_f32_32x32x16_bf16 v[80:95], v[64:67], v[108:111], 0
	v_exp_f32_e32 v120, v127
	v_exp_f32_e32 v121, v124
	v_exp_f32_e32 v122, v125
	s_waitcnt lgkmcnt(0)
	v_mfma_f32_32x32x16_bf16 v[64:79], v[68:71], v[108:111], 0
	ds_read_b128 v[108:111], v113 offset:49152
	ds_read_b128 v[114:117], v113 offset:53248
	v_exp_f32_e32 v113, v132
	s_waitcnt lgkmcnt(1)
	v_mfma_f32_32x32x16_bf16 v[80:95], v[108:111], v[104:107], v[80:95]
	v_add_u32_e32 v108, s45, v177
	s_waitcnt lgkmcnt(0)
	v_mfma_f32_32x32x16_bf16 v[64:79], v[114:117], v[104:107], v[64:79]
	ds_read_b128 v[104:107], v108 offset:49152
	ds_read_b128 v[108:111], v108 offset:53248
	v_exp_f32_e32 v114, v133
	v_exp_f32_e32 v115, v130
	v_exp_f32_e32 v116, v131
	v_exp_f32_e32 v117, v128
	s_waitcnt lgkmcnt(1)
	v_mfma_f32_32x32x16_bf16 v[80:95], v[104:107], v[100:103], v[80:95]
	v_add_u32_e32 v104, s45, v176
	s_waitcnt lgkmcnt(0)
	v_mfma_f32_32x32x16_bf16 v[64:79], v[108:111], v[100:103], v[64:79]
	ds_read_b128 v[100:103], v104 offset:49152
	ds_read_b128 v[104:107], v104 offset:53248
	v_exp_f32_e32 v108, v136
	v_exp_f32_e32 v109, v137
	v_exp_f32_e32 v110, v134
	v_exp_f32_e32 v111, v135
	s_waitcnt lgkmcnt(1)
	v_mfma_f32_32x32x16_bf16 v[80:95], v[100:103], v[96:99], v[80:95]
	v_cvt_pk_bf16_f32 v100, v168, v217
	v_cvt_pk_bf16_f32 v101, v169, v218
	v_cvt_pk_bf16_f32 v102, v142, v146
	v_cvt_pk_bf16_f32 v103, v143, v147
	s_waitcnt lgkmcnt(0)
	v_mfma_f32_32x32x16_bf16 v[64:79], v[104:107], v[96:99], v[64:79]
	v_add_f32_e32 v96, v170, v150
	v_add_f32_e32 v96, v151, v96
	v_add_f32_e32 v96, v171, v96
	v_add_f32_e32 v96, v168, v96
	v_add_f32_e32 v96, v217, v96
	v_add_f32_e32 v96, v169, v96
	v_add_f32_e32 v96, v218, v96
	v_add_f32_e32 v96, v142, v96
	v_add_f32_e32 v96, v146, v96
	v_add_f32_e32 v96, v143, v96
	v_add_f32_e32 v96, v147, v96
	v_exp_f32_e32 v106, v138
	v_add_f32_e32 v96, v144, v96
	v_exp_f32_e32 v107, v139
	v_add_f32_e32 v96, v148, v96
	v_add_f32_e32 v96, v145, v96
	v_add_f32_e32 v96, v149, v96
	v_add_f32_e32 v96, v106, v96
	v_add_f32_e32 v96, v107, v96
	v_add_f32_e32 v96, v108, v96
	v_add_f32_e32 v96, v109, v96
	v_add_f32_e32 v96, v110, v96
	v_add_f32_e32 v96, v111, v96
	v_add_f32_e32 v96, v113, v96
	v_add_f32_e32 v96, v114, v96
	v_add_f32_e32 v96, v115, v96
	v_add_f32_e32 v96, v116, v96
	v_add_f32_e32 v96, v117, v96
	v_add_f32_e32 v96, v118, v96
	v_add_f32_e32 v96, v119, v96
	v_add_f32_e32 v96, v120, v96
	v_add_f32_e32 v96, v121, v96
	v_add_f32_e32 v96, v122, v96
	v_mov_b32_e32 v97, v96
	v_cvt_pk_bf16_f32 v98, v150, v170
	v_cvt_pk_bf16_f32 v99, v151, v171
	s_nop 1
	v_permlane32_swap_b32_e32 v96, v97
	v_permlane32_swap_b32_e32 v98, v100
	v_permlane32_swap_b32_e32 v99, v101
	v_cvt_pk_bf16_f32 v104, v144, v148
	v_cvt_pk_bf16_f32 v105, v145, v149
	v_cvt_pk_bf16_f32 v106, v106, v107
	v_cvt_pk_bf16_f32 v107, v108, v109
	v_cvt_pk_bf16_f32 v108, v110, v111
	v_cvt_pk_bf16_f32 v109, v113, v114
	v_cvt_pk_bf16_f32 v114, v115, v116
	v_cvt_pk_bf16_f32 v115, v117, v118
	v_cvt_pk_bf16_f32 v116, v119, v120
	v_cvt_pk_bf16_f32 v117, v121, v122
	s_nop 0
	v_permlane32_swap_b32_e32 v102, v104
	v_permlane32_swap_b32_e32 v103, v105
	v_permlane32_swap_b32_e32 v106, v108
	v_permlane32_swap_b32_e32 v107, v109
	v_permlane32_swap_b32_e32 v114, v116
	v_permlane32_swap_b32_e32 v115, v117
	v_add_u32_e32 v110, s50, v112
	ds_read_b64_tr_b16 v[118:119], v110 offset:0
	ds_read_b64_tr_b16 v[120:121], v110 offset:0x800
	ds_read_b64_tr_b16 v[122:123], v110 offset:0x1000
	ds_read_b64_tr_b16 v[124:125], v110 offset:0x1800
	ds_read_b64_tr_b16 v[126:127], v110 offset:0x2000
	ds_read_b64_tr_b16 v[128:129], v110 offset:0x2800
	ds_read_b64_tr_b16 v[130:131], v110 offset:0x3000
	ds_read_b64_tr_b16 v[132:133], v110 offset:0x3800
	s_waitcnt lgkmcnt(0)
	s_nop 0
	v_mfma_f32_32x32x16_bf16 v[0:15], v[98:101], v[118:121], v[0:15]
	ds_read_b64_tr_b16 v[118:119], v110 offset:0x200
	ds_read_b64_tr_b16 v[120:121], v110 offset:0xa00
	v_mfma_f32_32x32x16_bf16 v[0:15], v[102:105], v[122:125], v[0:15]
	ds_read_b64_tr_b16 v[122:123], v110 offset:0x1200
	ds_read_b64_tr_b16 v[124:125], v110 offset:0x1a00
	v_mfma_f32_32x32x16_bf16 v[0:15], v[106:109], v[126:129], v[0:15]
	ds_read_b64_tr_b16 v[126:127], v110 offset:0x2200
	ds_read_b64_tr_b16 v[128:129], v110 offset:0x2a00
	v_mfma_f32_32x32x16_bf16 v[0:15], v[114:117], v[130:133], v[0:15]
	ds_read_b64_tr_b16 v[130:131], v110 offset:0x3200
	ds_read_b64_tr_b16 v[132:133], v110 offset:0x3a00
	s_waitcnt lgkmcnt(0)
; #define RESC(a) do { if (__any((a) < 1.f)) { if (hi == 0) al_l[r32] = (a); asm volatile("s_waitcnt lgkmcnt(0)" ::: "memory"); \
;     for (int d = 0; d < 4; ++d) for (int r = 0; r < 16; ++r) o[d][r] *= al_l[crow(r, hi)]; } } while (0)
; DEV void partialSM(f32x16& p0, f32x16& p1, float& m_reg, float& mn, float& alpha) {
;   constexpr float C = AT_SCALE * 1.4426950408889634f;
;   float pmax = p0[0];
; #pragma unroll
;   for (int r = 1; r < 16; ++r) pmax = fmaxf(pmax, p0[r]);
; #pragma unroll
;   for (int r = 0; r < 16; ++r) pmax = fmaxf(pmax, p1[r]);
;   { auto rr = __builtin_amdgcn_permlane32_swap(__float_as_uint(pmax), __float_as_uint(pmax), false, false);
;     pmax = fmaxf(__uint_as_float(rr[0]), __uint_as_float(rr[1])); }
;   if (__builtin_expect(__all(pmax - m_reg <= AT_THR / AT_SCALE), 1)) { mn = m_reg; alpha = 1.f; }
;   else { mn = fmaxf(m_reg, pmax); alpha = __builtin_amdgcn_exp2f((m_reg - mn) * C); m_reg = mn; }
; DEV void attn_pass(const u16* __restrict__ Qb, const u16* __restrict__ Kh, const u16* __restrict__ Vh, int seq, f32x16* o, float* rli) {
;     ...
;     pv_d0(o, vb0 + bp * AT_SHM_V, pa0, pa1, pa2, pa3); partialSM(pB0, pB1, m_reg, mnB, alB);
;     RESC(alB);
	v_mfma_f32_32x32x16_bf16 v[48:63], v[98:101], v[118:121], v[48:63]
	ds_read_b64_tr_b16 v[118:119], v110 offset:0x400
	ds_read_b64_tr_b16 v[120:121], v110 offset:0xc00
	v_mfma_f32_32x32x16_bf16 v[48:63], v[102:105], v[122:125], v[48:63]
	ds_read_b64_tr_b16 v[122:123], v110 offset:0x1400
	ds_read_b64_tr_b16 v[124:125], v110 offset:0x1c00
	v_mfma_f32_32x32x16_bf16 v[48:63], v[106:109], v[126:129], v[48:63]
	ds_read_b64_tr_b16 v[126:127], v110 offset:0x2400
	ds_read_b64_tr_b16 v[128:129], v110 offset:0x2c00
	v_mfma_f32_32x32x16_bf16 v[48:63], v[114:117], v[130:133], v[48:63]
	ds_read_b64_tr_b16 v[130:131], v110 offset:0x3400
	ds_read_b64_tr_b16 v[132:133], v110 offset:0x3c00
	s_waitcnt lgkmcnt(0)
	v_mfma_f32_32x32x16_bf16 v[32:47], v[98:101], v[118:121], v[32:47]
	ds_read_b64_tr_b16 v[118:119], v110 offset:0x600
	ds_read_b64_tr_b16 v[120:121], v110 offset:0xe00
	v_mfma_f32_32x32x16_bf16 v[32:47], v[102:105], v[122:125], v[32:47]
	ds_read_b64_tr_b16 v[122:123], v110 offset:0x1600
	ds_read_b64_tr_b16 v[124:125], v110 offset:0x1e00
	v_mfma_f32_32x32x16_bf16 v[32:47], v[106:109], v[126:129], v[32:47]
	ds_read_b64_tr_b16 v[126:127], v110 offset:0x2600
	ds_read_b64_tr_b16 v[128:129], v110 offset:0x2e00
	v_mfma_f32_32x32x16_bf16 v[32:47], v[114:117], v[130:133], v[32:47]
	ds_read_b64_tr_b16 v[130:131], v110 offset:0x3600
	ds_read_b64_tr_b16 v[132:133], v110 offset:0x3e00
	s_waitcnt lgkmcnt(0)
	v_mfma_f32_32x32x16_bf16 v[16:31], v[98:101], v[118:121], v[16:31]
	v_max_f32_e32 v98, v81, v81
	v_max_f32_e32 v99, v80, v80
	v_max_f32_e32 v98, v99, v98
	v_max3_f32 v98, v98, v82, v83
	v_max3_f32 v98, v98, v84, v85
	v_max3_f32 v98, v98, v86, v87
	v_max3_f32 v98, v98, v88, v89
	v_max3_f32 v98, v98, v90, v91
	v_max3_f32 v98, v98, v92, v93
	v_mfma_f32_32x32x16_bf16 v[16:31], v[102:105], v[122:125], v[16:31]
	v_max3_f32 v98, v98, v94, v95
	v_max3_f32 v98, v98, v64, v65
	v_max3_f32 v98, v98, v66, v67
	v_max3_f32 v98, v98, v68, v69
	v_max3_f32 v98, v98, v70, v71
	v_max3_f32 v98, v98, v72, v73
	v_max3_f32 v98, v98, v74, v75
	v_max3_f32 v98, v98, v76, v77
	v_mfma_f32_32x32x16_bf16 v[16:31], v[106:109], v[126:129], v[16:31]
	v_max3_f32 v98, v98, v78, v79
	v_mov_b32_e32 v99, v98
	s_nop 1
	v_permlane32_swap_b32_e32 v98, v99
	v_max_f32_e32 v99, v99, v99
	v_max_f32_e32 v98, v98, v98
	v_max_f32_e32 v98, v98, v99
	v_sub_f32_e32 v99, v98, v140
	v_cmp_ge_f32_e32 vcc, s18, v99
	v_max_f32_e32 v99, v140, v140
	v_max_f32_e32 v99, v99, v98
	v_mfma_f32_32x32x16_bf16 v[16:31], v[114:117], v[130:133], v[16:31]
	v_sub_f32_e32 v98, v140, v99
	v_mul_f32_e32 v98, 0x3e38aa3b, v98
	v_exp_f32_e32 v98, v98
	s_cmp_eq_u64 vcc, exec
	s_cselect_b64 s[0:1], -1, 0
	v_cndmask_b32_e64 v98, v98, 1.0, s[0:1]
	v_cmp_gt_f32_e32 vcc, 1.0, v98
	s_cbranch_vccz .LBB0_106
	s_mov_b64 s[8:9], exec
	s_and_b64 s[10:11], s[8:9], s[6:7]
	s_movk_i32 s45, 0x2000
	v_mov_b32_e32 v175, v235
	v_mov_b32_e32 v176, 0xb9500d01
	v_mov_b32_e32 v178, 0x37d00d01
	v_mov_b32_e32 v177, v236
	s_mov_b64 exec, s[10:11]
	ds_write_b32 v173, v98 offset:128
	s_or_b64 exec, exec, s[8:9]
	s_waitcnt lgkmcnt(0)
	v_add_u32_e32 v113, v157, v156
	ds_read_b128 v[100:103], v113 offset:224
	ds_read_b128 v[104:107], v113 offset:192
	ds_read_b128 v[108:111], v113 offset:160
	ds_read_b128 v[114:117], v113 offset:128
	s_waitcnt lgkmcnt(3)
	v_pk_mul_f32 v[12:13], v[12:13], v[100:101]
	s_waitcnt lgkmcnt(2)
	v_pk_mul_f32 v[8:9], v[8:9], v[104:105]
	s_waitcnt lgkmcnt(1)
	v_pk_mul_f32 v[4:5], v[4:5], v[108:109]
	v_pk_mul_f32 v[14:15], v[14:15], v[102:103]
	v_pk_mul_f32 v[10:11], v[10:11], v[106:107]
	v_pk_mul_f32 v[6:7], v[6:7], v[110:111]
	s_waitcnt lgkmcnt(0)
	v_pk_mul_f32 v[2:3], v[2:3], v[116:117]
	v_pk_mul_f32 v[0:1], v[0:1], v[114:115]
	v_pk_mul_f32 v[60:61], v[60:61], v[100:101]
	v_pk_mul_f32 v[56:57], v[56:57], v[104:105]
	v_pk_mul_f32 v[52:53], v[52:53], v[108:109]
	v_pk_mul_f32 v[62:63], v[62:63], v[102:103]
	v_pk_mul_f32 v[58:59], v[58:59], v[106:107]
	v_pk_mul_f32 v[54:55], v[54:55], v[110:111]
	v_pk_mul_f32 v[50:51], v[50:51], v[116:117]
	v_pk_mul_f32 v[48:49], v[48:49], v[114:115]
	v_pk_mul_f32 v[44:45], v[44:45], v[100:101]
	v_pk_mul_f32 v[40:41], v[40:41], v[104:105]
	v_pk_mul_f32 v[36:37], v[36:37], v[108:109]
	v_pk_mul_f32 v[46:47], v[46:47], v[102:103]
	v_pk_mul_f32 v[42:43], v[42:43], v[106:107]
	v_pk_mul_f32 v[38:39], v[38:39], v[110:111]
	v_pk_mul_f32 v[34:35], v[34:35], v[116:117]
	v_pk_mul_f32 v[32:33], v[32:33], v[114:115]
	v_pk_mul_f32 v[28:29], v[28:29], v[100:101]
	v_pk_mul_f32 v[24:25], v[24:25], v[104:105]
	v_pk_mul_f32 v[20:21], v[20:21], v[108:109]
	v_pk_mul_f32 v[30:31], v[30:31], v[102:103]
	v_pk_mul_f32 v[26:27], v[26:27], v[106:107]
	v_pk_mul_f32 v[22:23], v[22:23], v[110:111]
	v_pk_mul_f32 v[18:19], v[18:19], v[116:117]
	v_pk_mul_f32 v[16:17], v[16:17], v[114:115]
	s_branch .LBB0_107
